# K-loop MFMAs reordered in snake order so consecutive MFMAs share an operand (timing-only, same accumulation order per accumulator)
# baseline (speedup 1.0000x reference)
.LBB0_368:
	ds_read_b128 v[114:117], v197
	ds_read_b128 v[134:137], v197 offset:1024
	ds_read_b128 v[138:141], v197 offset:2048
	ds_read_b128 v[142:145], v197 offset:3072
	ds_read_b128 v[146:149], v198
	ds_read_b128 v[150:153], v198 offset:1024
	ds_read_b128 v[154:157], v198 offset:2048
	ds_read_b128 v[158:161], v198 offset:3072
	s_add_u32 s0, s6, 0xfffc0080
	s_addc_u32 s8, s7, -1
	s_cmp_eq_u32 s26, 12
	s_cselect_b32 s11, s2, s8
	s_cselect_b32 s10, s3, s0
	s_cselect_b32 s9, s12, s25
	s_cselect_b32 s8, s13, s24
	v_lshl_add_u64 v[230:231], s[6:7], 0, v[180:181]
	s_add_i32 m0, s31, 0xc000
	ds_read_b128 v[184:187], v199
	ds_read_b128 v[188:191], v199 offset:1024
	ds_read_b128 v[206:209], v199 offset:2048
	ds_read_b128 v[210:213], v199 offset:3072
	ds_read_b128 v[214:217], v199 offset:4096
	ds_read_b128 v[218:221], v199 offset:5120
	ds_read_b128 v[222:225], v199 offset:6144
	ds_read_b128 v[226:229], v199 offset:7168
	global_load_lds_dwordx4 v[230:231], off
	v_lshl_add_u64 v[230:231], s[6:7], 0, v[182:183]
	s_add_i32 m0, s31, 0xe000
	s_nop 0
	global_load_lds_dwordx4 v[230:231], off
	s_waitcnt vmcnt(8)
	s_waitcnt lgkmcnt(0)
	s_barrier
	s_setprio 1
	s_waitcnt lgkmcnt(0)
	v_mfma_f32_16x16x32_bf16 v[130:133], v[114:117], v[184:187], v[130:133]
	v_mfma_f32_16x16x32_bf16 v[126:129], v[138:141], v[184:187], v[126:129]
	v_mfma_f32_16x16x32_bf16 v[106:109], v[138:141], v[206:209], v[106:109]
	v_mfma_f32_16x16x32_bf16 v[110:113], v[114:117], v[206:209], v[110:113]
	v_mfma_f32_16x16x32_bf16 v[94:97], v[114:117], v[214:217], v[94:97]
	v_mfma_f32_16x16x32_bf16 v[90:93], v[138:141], v[214:217], v[90:93]
	v_mfma_f32_16x16x32_bf16 v[74:77], v[138:141], v[222:225], v[74:77]
	v_mfma_f32_16x16x32_bf16 v[78:81], v[114:117], v[222:225], v[78:81]
	v_mfma_f32_16x16x32_bf16 v[130:133], v[134:137], v[188:191], v[130:133]
	v_mfma_f32_16x16x32_bf16 v[126:129], v[142:145], v[188:191], v[126:129]
	v_mfma_f32_16x16x32_bf16 v[106:109], v[142:145], v[210:213], v[106:109]
	v_mfma_f32_16x16x32_bf16 v[110:113], v[134:137], v[210:213], v[110:113]
	v_mfma_f32_16x16x32_bf16 v[94:97], v[134:137], v[218:221], v[94:97]
	v_mfma_f32_16x16x32_bf16 v[90:93], v[142:145], v[218:221], v[90:93]
	v_mfma_f32_16x16x32_bf16 v[74:77], v[142:145], v[226:229], v[74:77]
	v_mfma_f32_16x16x32_bf16 v[78:81], v[134:137], v[226:229], v[78:81]
	s_setprio 0
	s_setprio 1
	v_mfma_f32_16x16x32_bf16 v[122:125], v[146:149], v[184:187], v[122:125]
	v_mfma_f32_16x16x32_bf16 v[118:121], v[154:157], v[184:187], v[118:121]
	v_mfma_f32_16x16x32_bf16 v[98:101], v[154:157], v[206:209], v[98:101]
	v_mfma_f32_16x16x32_bf16 v[102:105], v[146:149], v[206:209], v[102:105]
	v_mfma_f32_16x16x32_bf16 v[86:89], v[146:149], v[214:217], v[86:89]
	v_mfma_f32_16x16x32_bf16 v[82:85], v[154:157], v[214:217], v[82:85]
	v_mfma_f32_16x16x32_bf16 v[66:69], v[154:157], v[222:225], v[66:69]
	v_mfma_f32_16x16x32_bf16 v[70:73], v[146:149], v[222:225], v[70:73]
	v_mfma_f32_16x16x32_bf16 v[122:125], v[150:153], v[188:191], v[122:125]
	v_mfma_f32_16x16x32_bf16 v[118:121], v[158:161], v[188:191], v[118:121]
	v_mfma_f32_16x16x32_bf16 v[98:101], v[158:161], v[210:213], v[98:101]
	v_mfma_f32_16x16x32_bf16 v[102:105], v[150:153], v[210:213], v[102:105]
	v_mfma_f32_16x16x32_bf16 v[86:89], v[150:153], v[218:221], v[86:89]
	v_mfma_f32_16x16x32_bf16 v[82:85], v[158:161], v[218:221], v[82:85]
	v_mfma_f32_16x16x32_bf16 v[66:69], v[158:161], v[226:229], v[66:69]
	v_mfma_f32_16x16x32_bf16 v[70:73], v[150:153], v[226:229], v[70:73]
	s_setprio 0
	s_barrier
	s_add_i32 s0, s89, s79
	v_lshl_add_u64 v[230:231], s[8:9], 0, v[164:165]
	s_mov_b32 m0, s0
	ds_read_b128 v[184:187], v199 offset:16384
	ds_read_b128 v[188:191], v199 offset:17408
	ds_read_b128 v[206:209], v199 offset:18432
	ds_read_b128 v[210:213], v199 offset:19456
	ds_read_b128 v[214:217], v199 offset:20480
	ds_read_b128 v[218:221], v199 offset:21504
	ds_read_b128 v[222:225], v199 offset:22528
	ds_read_b128 v[226:229], v199 offset:23552
	global_load_lds_dwordx4 v[230:231], off
	s_add_i32 m0, s0, 0x2000
	s_add_u32 s62, s8, 0x40000
	v_lshl_add_u64 v[232:233], s[8:9], 0, v[168:169]
	s_addc_u32 s63, s9, 0
	s_add_i32 s0, s90, s79
	global_load_lds_dwordx4 v[232:233], off
	v_lshl_add_u64 v[234:235], s[62:63], 0, v[164:165]
	s_mov_b32 m0, s0
	v_lshl_add_u64 v[236:237], s[10:11], 0, v[166:167]
	global_load_lds_dwordx4 v[234:235], off
	v_lshl_add_u64 v[234:235], s[62:63], 0, v[168:169]
	s_add_i32 m0, s0, 0x2000
	s_nop 0
	global_load_lds_dwordx4 v[234:235], off
	v_lshl_add_u64 v[234:235], s[10:11], 0, v[162:163]
	s_mov_b32 m0, s31
	s_nop 0
	global_load_lds_dwordx4 v[234:235], off
	s_mov_b32 m0, s80
	s_nop 0
	global_load_lds_dwordx4 v[236:237], off
	s_waitcnt vmcnt(8)
	s_waitcnt lgkmcnt(0)
	s_barrier
	s_setprio 1
	s_waitcnt lgkmcnt(0)
	v_mfma_f32_16x16x32_bf16 v[62:65], v[114:117], v[184:187], v[62:65]
	v_mfma_f32_16x16x32_bf16 v[58:61], v[138:141], v[184:187], v[58:61]
	v_mfma_f32_16x16x32_bf16 v[42:45], v[138:141], v[206:209], v[42:45]
	v_mfma_f32_16x16x32_bf16 v[46:49], v[114:117], v[206:209], v[46:49]
	v_mfma_f32_16x16x32_bf16 v[30:33], v[114:117], v[214:217], v[30:33]
	v_mfma_f32_16x16x32_bf16 v[26:29], v[138:141], v[214:217], v[26:29]
	v_mfma_f32_16x16x32_bf16 v[10:13], v[138:141], v[222:225], v[10:13]
	v_mfma_f32_16x16x32_bf16 v[14:17], v[114:117], v[222:225], v[14:17]
	v_mfma_f32_16x16x32_bf16 v[62:65], v[134:137], v[188:191], v[62:65]
	v_mfma_f32_16x16x32_bf16 v[58:61], v[142:145], v[188:191], v[58:61]
	v_mfma_f32_16x16x32_bf16 v[42:45], v[142:145], v[210:213], v[42:45]
	v_mfma_f32_16x16x32_bf16 v[46:49], v[134:137], v[210:213], v[46:49]
	v_mfma_f32_16x16x32_bf16 v[30:33], v[134:137], v[218:221], v[30:33]
	v_mfma_f32_16x16x32_bf16 v[26:29], v[142:145], v[218:221], v[26:29]
	v_mfma_f32_16x16x32_bf16 v[10:13], v[142:145], v[226:229], v[10:13]
	v_mfma_f32_16x16x32_bf16 v[14:17], v[134:137], v[226:229], v[14:17]
	s_setprio 0
	s_setprio 1
	v_mfma_f32_16x16x32_bf16 v[54:57], v[146:149], v[184:187], v[54:57]
	v_mfma_f32_16x16x32_bf16 v[50:53], v[154:157], v[184:187], v[50:53]
	v_mfma_f32_16x16x32_bf16 v[34:37], v[154:157], v[206:209], v[34:37]
	v_mfma_f32_16x16x32_bf16 v[38:41], v[146:149], v[206:209], v[38:41]
	v_mfma_f32_16x16x32_bf16 v[22:25], v[146:149], v[214:217], v[22:25]
	v_mfma_f32_16x16x32_bf16 v[18:21], v[154:157], v[214:217], v[18:21]
	v_mfma_f32_16x16x32_bf16 v[2:5], v[154:157], v[222:225], v[2:5]
	v_mfma_f32_16x16x32_bf16 v[6:9], v[146:149], v[222:225], v[6:9]
	v_mfma_f32_16x16x32_bf16 v[54:57], v[150:153], v[188:191], v[54:57]
	v_mfma_f32_16x16x32_bf16 v[50:53], v[158:161], v[188:191], v[50:53]
	v_mfma_f32_16x16x32_bf16 v[34:37], v[158:161], v[210:213], v[34:37]
	v_mfma_f32_16x16x32_bf16 v[38:41], v[150:153], v[210:213], v[38:41]
	v_mfma_f32_16x16x32_bf16 v[22:25], v[150:153], v[218:221], v[22:25]
	v_mfma_f32_16x16x32_bf16 v[18:21], v[158:161], v[218:221], v[18:21]
	v_mfma_f32_16x16x32_bf16 v[2:5], v[158:161], v[226:229], v[2:5]
	v_mfma_f32_16x16x32_bf16 v[6:9], v[150:153], v[226:229], v[6:9]
	s_setprio 0
	s_barrier
	s_add_i32 s0, 0, 0x18000
	s_add_i32 s27, 0, 0x1c000
	v_add_u32_e32 v142, s0, v173
	v_add_u32_e32 v158, s27, v173
	ds_read_b128 v[114:117], v142
	ds_read_b128 v[134:137], v142 offset:1024
	ds_read_b128 v[138:141], v142 offset:2048
	ds_read_b128 v[142:145], v142 offset:3072
	ds_read_b128 v[146:149], v158
	ds_read_b128 v[150:153], v158 offset:1024
	ds_read_b128 v[154:157], v158 offset:2048
	ds_read_b128 v[158:161], v158 offset:3072
	s_add_u32 s10, s10, 0x40000
	s_addc_u32 s11, s11, 0
	s_mov_b32 m0, s81
	v_lshl_add_u64 v[238:239], s[10:11], 0, v[162:163]
	ds_read_b128 v[184:187], v199 offset:32768
	ds_read_b128 v[188:191], v199 offset:33792
	ds_read_b128 v[206:209], v199 offset:34816
	ds_read_b128 v[210:213], v199 offset:35840
	ds_read_b128 v[214:217], v199 offset:36864
	ds_read_b128 v[218:221], v199 offset:37888
	ds_read_b128 v[222:225], v199 offset:38912
	ds_read_b128 v[226:229], v199 offset:39936
	global_load_lds_dwordx4 v[238:239], off
	v_lshl_add_u64 v[238:239], s[10:11], 0, v[166:167]
	s_mov_b32 m0, s82
	s_nop 0
	global_load_lds_dwordx4 v[238:239], off
	s_waitcnt vmcnt(8)
	s_waitcnt lgkmcnt(0)
	s_barrier
	s_setprio 1
	s_waitcnt lgkmcnt(0)
	v_mfma_f32_16x16x32_bf16 v[130:133], v[114:117], v[184:187], v[130:133]
	v_mfma_f32_16x16x32_bf16 v[126:129], v[138:141], v[184:187], v[126:129]
	v_mfma_f32_16x16x32_bf16 v[106:109], v[138:141], v[206:209], v[106:109]
	v_mfma_f32_16x16x32_bf16 v[110:113], v[114:117], v[206:209], v[110:113]
	v_mfma_f32_16x16x32_bf16 v[94:97], v[114:117], v[214:217], v[94:97]
	v_mfma_f32_16x16x32_bf16 v[90:93], v[138:141], v[214:217], v[90:93]
	v_mfma_f32_16x16x32_bf16 v[74:77], v[138:141], v[222:225], v[74:77]
	v_mfma_f32_16x16x32_bf16 v[78:81], v[114:117], v[222:225], v[78:81]
	v_mfma_f32_16x16x32_bf16 v[130:133], v[134:137], v[188:191], v[130:133]
	v_mfma_f32_16x16x32_bf16 v[126:129], v[142:145], v[188:191], v[126:129]
	v_mfma_f32_16x16x32_bf16 v[106:109], v[142:145], v[210:213], v[106:109]
	v_mfma_f32_16x16x32_bf16 v[110:113], v[134:137], v[210:213], v[110:113]
	v_mfma_f32_16x16x32_bf16 v[94:97], v[134:137], v[218:221], v[94:97]
	v_mfma_f32_16x16x32_bf16 v[90:93], v[142:145], v[218:221], v[90:93]
	v_mfma_f32_16x16x32_bf16 v[74:77], v[142:145], v[226:229], v[74:77]
	v_mfma_f32_16x16x32_bf16 v[78:81], v[134:137], v[226:229], v[78:81]
	s_setprio 0
	s_setprio 1
	v_mfma_f32_16x16x32_bf16 v[122:125], v[146:149], v[184:187], v[122:125]
	v_mfma_f32_16x16x32_bf16 v[118:121], v[154:157], v[184:187], v[118:121]
	v_mfma_f32_16x16x32_bf16 v[98:101], v[154:157], v[206:209], v[98:101]
	v_mfma_f32_16x16x32_bf16 v[102:105], v[146:149], v[206:209], v[102:105]
	v_mfma_f32_16x16x32_bf16 v[86:89], v[146:149], v[214:217], v[86:89]
	v_mfma_f32_16x16x32_bf16 v[82:85], v[154:157], v[214:217], v[82:85]
	v_mfma_f32_16x16x32_bf16 v[66:69], v[154:157], v[222:225], v[66:69]
	v_mfma_f32_16x16x32_bf16 v[70:73], v[146:149], v[222:225], v[70:73]
	v_mfma_f32_16x16x32_bf16 v[122:125], v[150:153], v[188:191], v[122:125]
	v_mfma_f32_16x16x32_bf16 v[118:121], v[158:161], v[188:191], v[118:121]
	v_mfma_f32_16x16x32_bf16 v[98:101], v[158:161], v[210:213], v[98:101]
	v_mfma_f32_16x16x32_bf16 v[102:105], v[150:153], v[210:213], v[102:105]
	v_mfma_f32_16x16x32_bf16 v[86:89], v[150:153], v[218:221], v[86:89]
	v_mfma_f32_16x16x32_bf16 v[82:85], v[158:161], v[218:221], v[82:85]
	v_mfma_f32_16x16x32_bf16 v[66:69], v[158:161], v[226:229], v[66:69]
	v_mfma_f32_16x16x32_bf16 v[70:73], v[150:153], v[226:229], v[70:73]
	s_setprio 0
	s_barrier
	s_add_i32 s0, s0, s79
	v_lshl_add_u64 v[230:231], v[230:231], 0, s[42:43]
	s_mov_b32 m0, s0
	ds_read_b128 v[184:187], v199 offset:49152
	ds_read_b128 v[188:191], v199 offset:50176
	ds_read_b128 v[206:209], v199 offset:51200
	ds_read_b128 v[210:213], v199 offset:52224
	ds_read_b128 v[214:217], v199 offset:53248
	ds_read_b128 v[218:221], v199 offset:54272
	ds_read_b128 v[222:225], v199 offset:55296
	ds_read_b128 v[226:229], v199 offset:56320
	global_load_lds_dwordx4 v[230:231], off
	s_add_i32 m0, s0, 0x2000
	s_add_u32 s8, s8, 0x40080
	v_lshl_add_u64 v[230:231], v[232:233], 0, s[42:43]
	s_addc_u32 s9, s9, 0
	s_add_i32 s0, s27, s79
	global_load_lds_dwordx4 v[230:231], off
	v_lshl_add_u64 v[230:231], s[8:9], 0, v[164:165]
	s_mov_b32 m0, s0
	s_nop 0
	global_load_lds_dwordx4 v[230:231], off
	v_lshl_add_u64 v[230:231], s[8:9], 0, v[168:169]
	s_add_i32 m0, s0, 0x2000
	s_nop 0
	global_load_lds_dwordx4 v[230:231], off
	v_lshl_add_u64 v[230:231], v[234:235], 0, s[42:43]
	s_mov_b32 m0, s84
	s_nop 0
	global_load_lds_dwordx4 v[230:231], off
	v_lshl_add_u64 v[230:231], v[236:237], 0, s[42:43]
	s_mov_b32 m0, s85
	s_nop 0
	global_load_lds_dwordx4 v[230:231], off
	s_waitcnt vmcnt(8)
	s_waitcnt lgkmcnt(0)
	s_barrier
	s_setprio 1
	s_waitcnt lgkmcnt(0)
	v_mfma_f32_16x16x32_bf16 v[62:65], v[114:117], v[184:187], v[62:65]
	v_mfma_f32_16x16x32_bf16 v[58:61], v[138:141], v[184:187], v[58:61]
	v_mfma_f32_16x16x32_bf16 v[42:45], v[138:141], v[206:209], v[42:45]
	v_mfma_f32_16x16x32_bf16 v[46:49], v[114:117], v[206:209], v[46:49]
	v_mfma_f32_16x16x32_bf16 v[30:33], v[114:117], v[214:217], v[30:33]
	v_mfma_f32_16x16x32_bf16 v[26:29], v[138:141], v[214:217], v[26:29]
	v_mfma_f32_16x16x32_bf16 v[10:13], v[138:141], v[222:225], v[10:13]
	v_mfma_f32_16x16x32_bf16 v[14:17], v[114:117], v[222:225], v[14:17]
	v_mfma_f32_16x16x32_bf16 v[62:65], v[134:137], v[188:191], v[62:65]
	v_mfma_f32_16x16x32_bf16 v[58:61], v[142:145], v[188:191], v[58:61]
	v_mfma_f32_16x16x32_bf16 v[42:45], v[142:145], v[210:213], v[42:45]
	v_mfma_f32_16x16x32_bf16 v[46:49], v[134:137], v[210:213], v[46:49]
	v_mfma_f32_16x16x32_bf16 v[30:33], v[134:137], v[218:221], v[30:33]
	v_mfma_f32_16x16x32_bf16 v[26:29], v[142:145], v[218:221], v[26:29]
	v_mfma_f32_16x16x32_bf16 v[10:13], v[142:145], v[226:229], v[10:13]
	v_mfma_f32_16x16x32_bf16 v[14:17], v[134:137], v[226:229], v[14:17]
	s_setprio 0
	s_setprio 1
	v_mfma_f32_16x16x32_bf16 v[54:57], v[146:149], v[184:187], v[54:57]
	v_mfma_f32_16x16x32_bf16 v[50:53], v[154:157], v[184:187], v[50:53]
	v_mfma_f32_16x16x32_bf16 v[34:37], v[154:157], v[206:209], v[34:37]
	v_mfma_f32_16x16x32_bf16 v[38:41], v[146:149], v[206:209], v[38:41]
	v_mfma_f32_16x16x32_bf16 v[22:25], v[146:149], v[214:217], v[22:25]
	v_mfma_f32_16x16x32_bf16 v[18:21], v[154:157], v[214:217], v[18:21]
	v_mfma_f32_16x16x32_bf16 v[2:5], v[154:157], v[222:225], v[2:5]
	v_mfma_f32_16x16x32_bf16 v[6:9], v[146:149], v[222:225], v[6:9]
	v_mfma_f32_16x16x32_bf16 v[54:57], v[150:153], v[188:191], v[54:57]
	v_mfma_f32_16x16x32_bf16 v[50:53], v[158:161], v[188:191], v[50:53]
	v_mfma_f32_16x16x32_bf16 v[34:37], v[158:161], v[210:213], v[34:37]
	v_mfma_f32_16x16x32_bf16 v[38:41], v[150:153], v[210:213], v[38:41]
	v_mfma_f32_16x16x32_bf16 v[22:25], v[150:153], v[218:221], v[22:25]
	v_mfma_f32_16x16x32_bf16 v[18:21], v[158:161], v[218:221], v[18:21]
	v_mfma_f32_16x16x32_bf16 v[2:5], v[158:161], v[226:229], v[2:5]
	v_mfma_f32_16x16x32_bf16 v[6:9], v[150:153], v[226:229], v[6:9]
	s_setprio 0
	s_barrier
	s_add_i32 s26, s26, 2
	s_add_u32 s6, s6, 0x100
	s_addc_u32 s7, s7, 0
	s_add_u32 s24, s24, 0x100
	s_addc_u32 s25, s25, 0
	s_cmp_gt_u32 s26, 13
	s_cbranch_scc0 .LBB0_368
	s_and_b64 vcc, exec, s[46:47]
	s_cbranch_vccz .LBB0_371

.LBB0_390:
.LBB0_391:
	s_bitcmp1_b32 s46, 0
	s_cbranch_scc0 .Lae1_skip
	s_barrier

.LBB0_824:
	ds_read_b128 v[156:159], v185
	ds_read_b128 v[160:163], v185 offset:1024
	ds_read_b128 v[164:167], v185 offset:2048
	ds_read_b128 v[168:171], v185 offset:3072
	ds_read_b128 v[172:175], v186
	ds_read_b128 v[188:191], v186 offset:1024
	ds_read_b128 v[192:195], v186 offset:2048
	ds_read_b128 v[196:199], v186 offset:3072
	s_add_i32 s41, s41, 2
	v_lshl_add_u64 v[176:177], s[38:39], 0, v[154:155]
	v_lshl_add_u64 v[176:177], v[176:177], 0, s[44:45]
	v_lshl_add_u64 v[182:183], v[176:177], 0, s[22:23]
	s_add_i32 m0, s5, 0xc000
	ds_read_b128 v[200:203], v187
	ds_read_b128 v[204:207], v187 offset:1024
	ds_read_b128 v[208:211], v187 offset:2048
	ds_read_b128 v[212:215], v187 offset:3072
	ds_read_b128 v[216:219], v187 offset:4096
	ds_read_b128 v[220:223], v187 offset:5120
	ds_read_b128 v[224:227], v187 offset:6144
	ds_read_b128 v[228:231], v187 offset:7168
	global_load_lds_dwordx4 v[182:183], off
	v_lshl_add_u64 v[182:183], s[38:39], 0, v[150:151]
	v_lshl_add_u64 v[182:183], v[182:183], 0, s[44:45]
	v_lshl_add_u64 v[232:233], v[182:183], 0, s[22:23]
	s_add_i32 m0, s5, 0xe000
	s_nop 0
	global_load_lds_dwordx4 v[232:233], off
	s_waitcnt vmcnt(8)
	s_waitcnt lgkmcnt(0)
	s_barrier
	s_setprio 1
	s_waitcnt lgkmcnt(0)
	v_mfma_f32_16x16x32_bf16 v[70:73], v[156:159], v[200:203], v[70:73]
	v_mfma_f32_16x16x32_bf16 v[66:69], v[164:167], v[200:203], v[66:69]
	v_mfma_f32_16x16x32_bf16 v[94:97], v[164:167], v[208:211], v[94:97]
	v_mfma_f32_16x16x32_bf16 v[86:89], v[156:159], v[208:211], v[86:89]
	v_mfma_f32_16x16x32_bf16 v[110:113], v[156:159], v[216:219], v[110:113]
	v_mfma_f32_16x16x32_bf16 v[114:117], v[164:167], v[216:219], v[114:117]
	v_mfma_f32_16x16x32_bf16 v[102:105], v[164:167], v[224:227], v[102:105]
	v_mfma_f32_16x16x32_bf16 v[126:129], v[156:159], v[224:227], v[126:129]
	v_mfma_f32_16x16x32_bf16 v[70:73], v[160:163], v[204:207], v[70:73]
	v_mfma_f32_16x16x32_bf16 v[66:69], v[168:171], v[204:207], v[66:69]
	v_mfma_f32_16x16x32_bf16 v[94:97], v[168:171], v[212:215], v[94:97]
	v_mfma_f32_16x16x32_bf16 v[86:89], v[160:163], v[212:215], v[86:89]
	v_mfma_f32_16x16x32_bf16 v[110:113], v[160:163], v[220:223], v[110:113]
	v_mfma_f32_16x16x32_bf16 v[114:117], v[168:171], v[220:223], v[114:117]
	v_mfma_f32_16x16x32_bf16 v[102:105], v[168:171], v[228:231], v[102:105]
	v_mfma_f32_16x16x32_bf16 v[126:129], v[160:163], v[228:231], v[126:129]
	s_setprio 0
	s_setprio 1
	v_mfma_f32_16x16x32_bf16 v[74:77], v[172:175], v[200:203], v[74:77]
	v_mfma_f32_16x16x32_bf16 v[82:85], v[192:195], v[200:203], v[82:85]
	v_mfma_f32_16x16x32_bf16 v[106:109], v[192:195], v[208:211], v[106:109]
	v_mfma_f32_16x16x32_bf16 v[98:101], v[172:175], v[208:211], v[98:101]
	v_mfma_f32_16x16x32_bf16 v[118:121], v[172:175], v[216:219], v[118:121]
	v_mfma_f32_16x16x32_bf16 v[122:125], v[192:195], v[216:219], v[122:125]
	v_mfma_f32_16x16x32_bf16 v[78:81], v[192:195], v[224:227], v[78:81]
	v_mfma_f32_16x16x32_bf16 v[90:93], v[172:175], v[224:227], v[90:93]
	v_mfma_f32_16x16x32_bf16 v[74:77], v[188:191], v[204:207], v[74:77]
	v_mfma_f32_16x16x32_bf16 v[82:85], v[196:199], v[204:207], v[82:85]
	v_mfma_f32_16x16x32_bf16 v[106:109], v[196:199], v[212:215], v[106:109]
	v_mfma_f32_16x16x32_bf16 v[98:101], v[188:191], v[212:215], v[98:101]
	v_mfma_f32_16x16x32_bf16 v[118:121], v[188:191], v[220:223], v[118:121]
	v_mfma_f32_16x16x32_bf16 v[122:125], v[196:199], v[220:223], v[122:125]
	v_mfma_f32_16x16x32_bf16 v[78:81], v[196:199], v[228:231], v[78:81]
	v_mfma_f32_16x16x32_bf16 v[90:93], v[188:191], v[228:231], v[90:93]
	s_setprio 0
	s_barrier
	v_lshl_add_u64 v[232:233], s[36:37], 0, v[144:145]
	v_lshl_add_u64 v[232:233], v[232:233], 0, s[44:45]
	s_add_i32 s60, s57, s4
	v_lshl_add_u64 v[234:235], v[232:233], 0, s[26:27]
	s_mov_b32 m0, s60
	ds_read_b128 v[200:203], v187 offset:16384
	ds_read_b128 v[204:207], v187 offset:17408
	ds_read_b128 v[208:211], v187 offset:18432
	ds_read_b128 v[212:215], v187 offset:19456
	ds_read_b128 v[216:219], v187 offset:20480
	ds_read_b128 v[220:223], v187 offset:21504
	ds_read_b128 v[224:227], v187 offset:22528
	ds_read_b128 v[228:231], v187 offset:23552
	global_load_lds_dwordx4 v[234:235], off
	v_lshl_add_u64 v[234:235], s[36:37], 0, v[140:141]
	v_lshl_add_u64 v[234:235], v[234:235], 0, s[44:45]
	v_lshl_add_u64 v[236:237], v[234:235], 0, s[26:27]
	s_add_i32 m0, s60, 0x2000
	s_add_i32 s60, s58, s4
	global_load_lds_dwordx4 v[236:237], off
	v_lshl_add_u64 v[236:237], s[36:37], 0, v[146:147]
	v_lshl_add_u64 v[236:237], v[236:237], 0, s[44:45]
	v_lshl_add_u64 v[238:239], v[236:237], 0, s[26:27]
	s_mov_b32 m0, s60
	s_nop 0
	global_load_lds_dwordx4 v[238:239], off
	v_lshl_add_u64 v[238:239], s[36:37], 0, v[142:143]
	v_lshl_add_u64 v[238:239], v[238:239], 0, s[44:45]
	v_lshl_add_u64 v[240:241], v[238:239], 0, s[26:27]
	s_add_i32 m0, s60, 0x2000
	s_nop 0
	global_load_lds_dwordx4 v[240:241], off
	v_lshl_add_u64 v[240:241], s[38:39], 0, v[152:153]
	v_lshl_add_u64 v[240:241], v[240:241], 0, s[44:45]
	v_lshl_add_u64 v[242:243], v[240:241], 0, s[26:27]
	s_mov_b32 m0, s5
	s_nop 0
	global_load_lds_dwordx4 v[242:243], off
	v_lshl_add_u64 v[242:243], s[38:39], 0, v[148:149]
	v_lshl_add_u64 v[242:243], v[242:243], 0, s[44:45]
	v_lshl_add_u64 v[244:245], v[242:243], 0, s[26:27]
	s_mov_b32 m0, s46
	s_nop 0
	global_load_lds_dwordx4 v[244:245], off
	s_waitcnt vmcnt(8)
	s_waitcnt lgkmcnt(0)
	s_barrier
	s_setprio 1
	s_waitcnt lgkmcnt(0)
	v_mfma_f32_16x16x32_bf16 v[62:65], v[156:159], v[200:203], v[62:65]
	v_mfma_f32_16x16x32_bf16 v[58:61], v[164:167], v[200:203], v[58:61]
	v_mfma_f32_16x16x32_bf16 v[42:45], v[164:167], v[208:211], v[42:45]
	v_mfma_f32_16x16x32_bf16 v[46:49], v[156:159], v[208:211], v[46:49]
	v_mfma_f32_16x16x32_bf16 v[30:33], v[156:159], v[216:219], v[30:33]
	v_mfma_f32_16x16x32_bf16 v[26:29], v[164:167], v[216:219], v[26:29]
	v_mfma_f32_16x16x32_bf16 v[10:13], v[164:167], v[224:227], v[10:13]
	v_mfma_f32_16x16x32_bf16 v[14:17], v[156:159], v[224:227], v[14:17]
	v_mfma_f32_16x16x32_bf16 v[62:65], v[160:163], v[204:207], v[62:65]
	v_mfma_f32_16x16x32_bf16 v[58:61], v[168:171], v[204:207], v[58:61]
	v_mfma_f32_16x16x32_bf16 v[42:45], v[168:171], v[212:215], v[42:45]
	v_mfma_f32_16x16x32_bf16 v[46:49], v[160:163], v[212:215], v[46:49]
	v_mfma_f32_16x16x32_bf16 v[30:33], v[160:163], v[220:223], v[30:33]
	v_mfma_f32_16x16x32_bf16 v[26:29], v[168:171], v[220:223], v[26:29]
	v_mfma_f32_16x16x32_bf16 v[10:13], v[168:171], v[228:231], v[10:13]
	v_mfma_f32_16x16x32_bf16 v[14:17], v[160:163], v[228:231], v[14:17]
	s_setprio 0
	s_setprio 1
	v_mfma_f32_16x16x32_bf16 v[54:57], v[172:175], v[200:203], v[54:57]
	v_mfma_f32_16x16x32_bf16 v[50:53], v[192:195], v[200:203], v[50:53]
	v_mfma_f32_16x16x32_bf16 v[34:37], v[192:195], v[208:211], v[34:37]
	v_mfma_f32_16x16x32_bf16 v[38:41], v[172:175], v[208:211], v[38:41]
	v_mfma_f32_16x16x32_bf16 v[22:25], v[172:175], v[216:219], v[22:25]
	v_mfma_f32_16x16x32_bf16 v[18:21], v[192:195], v[216:219], v[18:21]
	v_mfma_f32_16x16x32_bf16 v[2:5], v[192:195], v[224:227], v[2:5]
	v_mfma_f32_16x16x32_bf16 v[6:9], v[172:175], v[224:227], v[6:9]
	v_mfma_f32_16x16x32_bf16 v[54:57], v[188:191], v[204:207], v[54:57]
	v_mfma_f32_16x16x32_bf16 v[50:53], v[196:199], v[204:207], v[50:53]
	v_mfma_f32_16x16x32_bf16 v[34:37], v[196:199], v[212:215], v[34:37]
	v_mfma_f32_16x16x32_bf16 v[38:41], v[188:191], v[212:215], v[38:41]
	v_mfma_f32_16x16x32_bf16 v[22:25], v[188:191], v[220:223], v[22:25]
	v_mfma_f32_16x16x32_bf16 v[18:21], v[196:199], v[220:223], v[18:21]
	v_mfma_f32_16x16x32_bf16 v[2:5], v[196:199], v[228:231], v[2:5]
	v_mfma_f32_16x16x32_bf16 v[6:9], v[188:191], v[228:231], v[6:9]
	s_setprio 0
	s_barrier
	s_add_i32 s60, 0, 0x18000
	v_add_u32_e32 v138, s60, v181
	s_add_i32 s61, 0, 0x1c000
	ds_read_b128 v[156:159], v138
	ds_read_b128 v[160:163], v138 offset:1024
	ds_read_b128 v[164:167], v138 offset:2048
	ds_read_b128 v[168:171], v138 offset:3072
	v_add_u32_e32 v138, s61, v181
	ds_read_b128 v[172:175], v138
	ds_read_b128 v[188:191], v138 offset:1024
	ds_read_b128 v[192:195], v138 offset:2048
	ds_read_b128 v[196:199], v138 offset:3072
	s_mov_b32 m0, s47
	v_lshl_add_u64 v[176:177], v[176:177], 0, s[26:27]
	ds_read_b128 v[200:203], v187 offset:32768
	ds_read_b128 v[204:207], v187 offset:33792
	ds_read_b128 v[208:211], v187 offset:34816
	ds_read_b128 v[212:215], v187 offset:35840
	ds_read_b128 v[216:219], v187 offset:36864
	ds_read_b128 v[220:223], v187 offset:37888
	ds_read_b128 v[224:227], v187 offset:38912
	ds_read_b128 v[228:231], v187 offset:39936
	global_load_lds_dwordx4 v[176:177], off
	v_lshl_add_u64 v[176:177], v[182:183], 0, s[26:27]
	s_mov_b32 m0, s48
	s_nop 0
	global_load_lds_dwordx4 v[176:177], off
	s_waitcnt vmcnt(8)
	s_waitcnt lgkmcnt(0)
	s_barrier
	s_setprio 1
	s_waitcnt lgkmcnt(0)
	v_mfma_f32_16x16x32_bf16 v[70:73], v[156:159], v[200:203], v[70:73]
	v_mfma_f32_16x16x32_bf16 v[66:69], v[164:167], v[200:203], v[66:69]
	v_mfma_f32_16x16x32_bf16 v[94:97], v[164:167], v[208:211], v[94:97]
	v_mfma_f32_16x16x32_bf16 v[86:89], v[156:159], v[208:211], v[86:89]
	v_mfma_f32_16x16x32_bf16 v[110:113], v[156:159], v[216:219], v[110:113]
	v_mfma_f32_16x16x32_bf16 v[114:117], v[164:167], v[216:219], v[114:117]
	v_mfma_f32_16x16x32_bf16 v[102:105], v[164:167], v[224:227], v[102:105]
	v_mfma_f32_16x16x32_bf16 v[126:129], v[156:159], v[224:227], v[126:129]
	v_mfma_f32_16x16x32_bf16 v[70:73], v[160:163], v[204:207], v[70:73]
	v_mfma_f32_16x16x32_bf16 v[66:69], v[168:171], v[204:207], v[66:69]
	v_mfma_f32_16x16x32_bf16 v[94:97], v[168:171], v[212:215], v[94:97]
	v_mfma_f32_16x16x32_bf16 v[86:89], v[160:163], v[212:215], v[86:89]
	v_mfma_f32_16x16x32_bf16 v[110:113], v[160:163], v[220:223], v[110:113]
	v_mfma_f32_16x16x32_bf16 v[114:117], v[168:171], v[220:223], v[114:117]
	v_mfma_f32_16x16x32_bf16 v[102:105], v[168:171], v[228:231], v[102:105]
	v_mfma_f32_16x16x32_bf16 v[126:129], v[160:163], v[228:231], v[126:129]
	s_setprio 0
	s_setprio 1
	v_mfma_f32_16x16x32_bf16 v[74:77], v[172:175], v[200:203], v[74:77]
	v_mfma_f32_16x16x32_bf16 v[82:85], v[192:195], v[200:203], v[82:85]
	v_mfma_f32_16x16x32_bf16 v[106:109], v[192:195], v[208:211], v[106:109]
	v_mfma_f32_16x16x32_bf16 v[98:101], v[172:175], v[208:211], v[98:101]
	v_mfma_f32_16x16x32_bf16 v[118:121], v[172:175], v[216:219], v[118:121]
	v_mfma_f32_16x16x32_bf16 v[122:125], v[192:195], v[216:219], v[122:125]
	v_mfma_f32_16x16x32_bf16 v[78:81], v[192:195], v[224:227], v[78:81]
	v_mfma_f32_16x16x32_bf16 v[90:93], v[172:175], v[224:227], v[90:93]
	v_mfma_f32_16x16x32_bf16 v[74:77], v[188:191], v[204:207], v[74:77]
	v_mfma_f32_16x16x32_bf16 v[82:85], v[196:199], v[204:207], v[82:85]
	v_mfma_f32_16x16x32_bf16 v[106:109], v[196:199], v[212:215], v[106:109]
	v_mfma_f32_16x16x32_bf16 v[98:101], v[188:191], v[212:215], v[98:101]
	v_mfma_f32_16x16x32_bf16 v[118:121], v[188:191], v[220:223], v[118:121]
	v_mfma_f32_16x16x32_bf16 v[122:125], v[196:199], v[220:223], v[122:125]
	v_mfma_f32_16x16x32_bf16 v[78:81], v[196:199], v[228:231], v[78:81]
	v_mfma_f32_16x16x32_bf16 v[90:93], v[188:191], v[228:231], v[90:93]
	s_setprio 0
	s_barrier
	s_add_i32 s60, s60, s4
	v_lshl_add_u64 v[176:177], v[232:233], 0, s[28:29]
	s_mov_b32 m0, s60
	ds_read_b128 v[200:203], v187 offset:49152
	ds_read_b128 v[204:207], v187 offset:50176
	ds_read_b128 v[208:211], v187 offset:51200
	ds_read_b128 v[212:215], v187 offset:52224
	ds_read_b128 v[216:219], v187 offset:53248
	ds_read_b128 v[220:223], v187 offset:54272
	ds_read_b128 v[224:227], v187 offset:55296
	ds_read_b128 v[228:231], v187 offset:56320
	global_load_lds_dwordx4 v[176:177], off
	v_lshl_add_u64 v[176:177], v[234:235], 0, s[28:29]
	s_add_i32 m0, s60, 0x2000
	s_add_i32 s60, s61, s4
	global_load_lds_dwordx4 v[176:177], off
	v_lshl_add_u64 v[176:177], v[236:237], 0, s[28:29]
	s_mov_b32 m0, s60
	s_nop 0
	global_load_lds_dwordx4 v[176:177], off
	v_lshl_add_u64 v[176:177], v[238:239], 0, s[28:29]
	s_add_i32 m0, s60, 0x2000
	s_nop 0
	global_load_lds_dwordx4 v[176:177], off
	v_lshl_add_u64 v[176:177], v[240:241], 0, s[28:29]
	s_mov_b32 m0, s49
	s_nop 0
	global_load_lds_dwordx4 v[176:177], off
	v_lshl_add_u64 v[176:177], v[242:243], 0, s[28:29]
	s_mov_b32 m0, s50
	s_nop 0
	global_load_lds_dwordx4 v[176:177], off
	s_waitcnt vmcnt(8)
	s_waitcnt lgkmcnt(0)
	s_barrier
	s_setprio 1
	s_waitcnt lgkmcnt(0)
	v_mfma_f32_16x16x32_bf16 v[62:65], v[156:159], v[200:203], v[62:65]
	v_mfma_f32_16x16x32_bf16 v[58:61], v[164:167], v[200:203], v[58:61]
	v_mfma_f32_16x16x32_bf16 v[42:45], v[164:167], v[208:211], v[42:45]
	v_mfma_f32_16x16x32_bf16 v[46:49], v[156:159], v[208:211], v[46:49]
	v_mfma_f32_16x16x32_bf16 v[30:33], v[156:159], v[216:219], v[30:33]
	v_mfma_f32_16x16x32_bf16 v[26:29], v[164:167], v[216:219], v[26:29]
	v_mfma_f32_16x16x32_bf16 v[10:13], v[164:167], v[224:227], v[10:13]
	v_mfma_f32_16x16x32_bf16 v[14:17], v[156:159], v[224:227], v[14:17]
	v_mfma_f32_16x16x32_bf16 v[62:65], v[160:163], v[204:207], v[62:65]
	v_mfma_f32_16x16x32_bf16 v[58:61], v[168:171], v[204:207], v[58:61]
	v_mfma_f32_16x16x32_bf16 v[42:45], v[168:171], v[212:215], v[42:45]
	v_mfma_f32_16x16x32_bf16 v[46:49], v[160:163], v[212:215], v[46:49]
	v_mfma_f32_16x16x32_bf16 v[30:33], v[160:163], v[220:223], v[30:33]
	v_mfma_f32_16x16x32_bf16 v[26:29], v[168:171], v[220:223], v[26:29]
	v_mfma_f32_16x16x32_bf16 v[10:13], v[168:171], v[228:231], v[10:13]
	v_mfma_f32_16x16x32_bf16 v[14:17], v[160:163], v[228:231], v[14:17]
	s_setprio 0
	s_setprio 1
	v_mfma_f32_16x16x32_bf16 v[54:57], v[172:175], v[200:203], v[54:57]
	v_mfma_f32_16x16x32_bf16 v[50:53], v[192:195], v[200:203], v[50:53]
	v_mfma_f32_16x16x32_bf16 v[34:37], v[192:195], v[208:211], v[34:37]
	v_mfma_f32_16x16x32_bf16 v[38:41], v[172:175], v[208:211], v[38:41]
	v_mfma_f32_16x16x32_bf16 v[22:25], v[172:175], v[216:219], v[22:25]
	v_mfma_f32_16x16x32_bf16 v[18:21], v[192:195], v[216:219], v[18:21]
	v_mfma_f32_16x16x32_bf16 v[2:5], v[192:195], v[224:227], v[2:5]
	v_mfma_f32_16x16x32_bf16 v[6:9], v[172:175], v[224:227], v[6:9]
	v_mfma_f32_16x16x32_bf16 v[54:57], v[188:191], v[204:207], v[54:57]
	v_mfma_f32_16x16x32_bf16 v[50:53], v[196:199], v[204:207], v[50:53]
	v_mfma_f32_16x16x32_bf16 v[34:37], v[196:199], v[212:215], v[34:37]
	v_mfma_f32_16x16x32_bf16 v[38:41], v[188:191], v[212:215], v[38:41]
	v_mfma_f32_16x16x32_bf16 v[22:25], v[188:191], v[220:223], v[22:25]
	v_mfma_f32_16x16x32_bf16 v[18:21], v[196:199], v[220:223], v[18:21]
	v_mfma_f32_16x16x32_bf16 v[2:5], v[196:199], v[228:231], v[2:5]
	v_mfma_f32_16x16x32_bf16 v[6:9], v[188:191], v[228:231], v[6:9]
	s_setprio 0
	s_barrier
	s_add_u32 s44, s44, 0x100
	s_addc_u32 s45, s45, 0
	s_cmp_ge_i32 s41, s40
	s_cbranch_scc0 .LBB0_824
	s_branch .LBB0_826

.LBB0_828:
	ds_read_b128 v[158:161], v185
	ds_read_b128 v[162:165], v185 offset:1024
	ds_read_b128 v[166:169], v185 offset:2048
	ds_read_b128 v[170:173], v185 offset:3072
	ds_read_b128 v[174:177], v186
	ds_read_b128 v[190:193], v186 offset:1024
	ds_read_b128 v[194:197], v186 offset:2048
	ds_read_b128 v[198:201], v186 offset:3072
	s_add_i32 s42, s40, 1
	s_ashr_i32 s43, s42, 31
	s_lshl_b64 s[44:45], s[42:43], 7
	s_add_i32 s42, s40, 2
	s_add_u32 s43, s38, s0
	s_addc_u32 s41, s39, s1
	s_add_u32 s60, s36, s0
	s_addc_u32 s61, s37, s1
	s_cmp_eq_u32 s52, s40
	s_cselect_b32 s41, s13, s41
	s_cselect_b32 s40, s12, s43
	s_cselect_b32 s61, s35, s61
	s_cselect_b32 s60, s34, s60
	s_add_u32 s43, s38, s44
	s_addc_u32 s45, s39, s45
	s_add_u32 s44, s43, s8
	s_addc_u32 s45, s45, s9
	v_lshl_add_u64 v[182:183], s[44:45], 0, v[136:137]
	s_add_i32 m0, s5, 0xc000
	ds_read_b128 v[202:205], v187
	ds_read_b128 v[206:209], v187 offset:1024
	ds_read_b128 v[210:213], v187 offset:2048
	ds_read_b128 v[214:217], v187 offset:3072
	ds_read_b128 v[218:221], v187 offset:4096
	ds_read_b128 v[222:225], v187 offset:5120
	ds_read_b128 v[226:229], v187 offset:6144
	ds_read_b128 v[230:233], v187 offset:7168
	global_load_lds_dwordx4 v[182:183], off
	v_lshl_add_u64 v[182:183], s[44:45], 0, v[132:133]
	s_add_i32 m0, s5, 0xe000
	s_nop 0
	global_load_lds_dwordx4 v[182:183], off
	s_waitcnt vmcnt(8)
	s_waitcnt lgkmcnt(0)
	s_barrier
	s_setprio 1
	s_waitcnt lgkmcnt(0)
	v_mfma_f32_16x16x32_bf16 v[70:73], v[158:161], v[202:205], v[70:73]
	v_mfma_f32_16x16x32_bf16 v[66:69], v[166:169], v[202:205], v[66:69]
	v_mfma_f32_16x16x32_bf16 v[94:97], v[166:169], v[210:213], v[94:97]
	v_mfma_f32_16x16x32_bf16 v[86:89], v[158:161], v[210:213], v[86:89]
	v_mfma_f32_16x16x32_bf16 v[110:113], v[158:161], v[218:221], v[110:113]
	v_mfma_f32_16x16x32_bf16 v[114:117], v[166:169], v[218:221], v[114:117]
	v_mfma_f32_16x16x32_bf16 v[102:105], v[166:169], v[226:229], v[102:105]
	v_mfma_f32_16x16x32_bf16 v[126:129], v[158:161], v[226:229], v[126:129]
	v_mfma_f32_16x16x32_bf16 v[70:73], v[162:165], v[206:209], v[70:73]
	v_mfma_f32_16x16x32_bf16 v[66:69], v[170:173], v[206:209], v[66:69]
	v_mfma_f32_16x16x32_bf16 v[94:97], v[170:173], v[214:217], v[94:97]
	v_mfma_f32_16x16x32_bf16 v[86:89], v[162:165], v[214:217], v[86:89]
	v_mfma_f32_16x16x32_bf16 v[110:113], v[162:165], v[222:225], v[110:113]
	v_mfma_f32_16x16x32_bf16 v[114:117], v[170:173], v[222:225], v[114:117]
	v_mfma_f32_16x16x32_bf16 v[102:105], v[170:173], v[230:233], v[102:105]
	v_mfma_f32_16x16x32_bf16 v[126:129], v[162:165], v[230:233], v[126:129]
	s_setprio 0
	s_setprio 1
	v_mfma_f32_16x16x32_bf16 v[74:77], v[174:177], v[202:205], v[74:77]
	v_mfma_f32_16x16x32_bf16 v[82:85], v[194:197], v[202:205], v[82:85]
	v_mfma_f32_16x16x32_bf16 v[106:109], v[194:197], v[210:213], v[106:109]
	v_mfma_f32_16x16x32_bf16 v[98:101], v[174:177], v[210:213], v[98:101]
	v_mfma_f32_16x16x32_bf16 v[118:121], v[174:177], v[218:221], v[118:121]
	v_mfma_f32_16x16x32_bf16 v[122:125], v[194:197], v[218:221], v[122:125]
	v_mfma_f32_16x16x32_bf16 v[78:81], v[194:197], v[226:229], v[78:81]
	v_mfma_f32_16x16x32_bf16 v[90:93], v[174:177], v[226:229], v[90:93]
	v_mfma_f32_16x16x32_bf16 v[74:77], v[190:193], v[206:209], v[74:77]
	v_mfma_f32_16x16x32_bf16 v[82:85], v[198:201], v[206:209], v[82:85]
	v_mfma_f32_16x16x32_bf16 v[106:109], v[198:201], v[214:217], v[106:109]
	v_mfma_f32_16x16x32_bf16 v[98:101], v[190:193], v[214:217], v[98:101]
	v_mfma_f32_16x16x32_bf16 v[118:121], v[190:193], v[222:225], v[118:121]
	v_mfma_f32_16x16x32_bf16 v[122:125], v[198:201], v[222:225], v[122:125]
	v_mfma_f32_16x16x32_bf16 v[78:81], v[198:201], v[230:233], v[78:81]
	v_mfma_f32_16x16x32_bf16 v[90:93], v[190:193], v[230:233], v[90:93]
	s_setprio 0
	s_barrier
	s_add_i32 s43, s57, s4
	v_lshl_add_u64 v[182:183], s[60:61], 0, v[134:135]
	s_mov_b32 m0, s43
	ds_read_b128 v[202:205], v187 offset:16384
	ds_read_b128 v[206:209], v187 offset:17408
	ds_read_b128 v[210:213], v187 offset:18432
	ds_read_b128 v[214:217], v187 offset:19456
	ds_read_b128 v[218:221], v187 offset:20480
	ds_read_b128 v[222:225], v187 offset:21504
	ds_read_b128 v[226:229], v187 offset:22528
	ds_read_b128 v[230:233], v187 offset:23552
	global_load_lds_dwordx4 v[182:183], off
	s_add_i32 m0, s43, 0x2000
	s_add_u32 s44, s60, s8
	v_lshl_add_u64 v[234:235], s[60:61], 0, v[130:131]
	s_addc_u32 s45, s61, s9
	s_add_i32 s43, s58, s4
	global_load_lds_dwordx4 v[234:235], off
	v_lshl_add_u64 v[236:237], s[44:45], 0, v[134:135]
	s_mov_b32 m0, s43
	v_lshl_add_u64 v[238:239], s[44:45], 0, v[130:131]
	global_load_lds_dwordx4 v[236:237], off
	s_add_i32 m0, s43, 0x2000
	v_lshl_add_u64 v[240:241], s[40:41], 0, v[136:137]
	global_load_lds_dwordx4 v[238:239], off
	s_mov_b32 m0, s5
	v_lshl_add_u64 v[242:243], s[40:41], 0, v[132:133]
	global_load_lds_dwordx4 v[240:241], off
	s_mov_b32 m0, s46
	s_nop 0
	global_load_lds_dwordx4 v[242:243], off
	s_waitcnt vmcnt(8)
	s_waitcnt lgkmcnt(0)
	s_barrier
	s_setprio 1
	s_waitcnt lgkmcnt(0)
	v_mfma_f32_16x16x32_bf16 v[62:65], v[158:161], v[202:205], v[62:65]
	v_mfma_f32_16x16x32_bf16 v[58:61], v[166:169], v[202:205], v[58:61]
	v_mfma_f32_16x16x32_bf16 v[42:45], v[166:169], v[210:213], v[42:45]
	v_mfma_f32_16x16x32_bf16 v[46:49], v[158:161], v[210:213], v[46:49]
	v_mfma_f32_16x16x32_bf16 v[30:33], v[158:161], v[218:221], v[30:33]
	v_mfma_f32_16x16x32_bf16 v[26:29], v[166:169], v[218:221], v[26:29]
	v_mfma_f32_16x16x32_bf16 v[10:13], v[166:169], v[226:229], v[10:13]
	v_mfma_f32_16x16x32_bf16 v[14:17], v[158:161], v[226:229], v[14:17]
	v_mfma_f32_16x16x32_bf16 v[62:65], v[162:165], v[206:209], v[62:65]
	v_mfma_f32_16x16x32_bf16 v[58:61], v[170:173], v[206:209], v[58:61]
	v_mfma_f32_16x16x32_bf16 v[42:45], v[170:173], v[214:217], v[42:45]
	v_mfma_f32_16x16x32_bf16 v[46:49], v[162:165], v[214:217], v[46:49]
	v_mfma_f32_16x16x32_bf16 v[30:33], v[162:165], v[222:225], v[30:33]
	v_mfma_f32_16x16x32_bf16 v[26:29], v[170:173], v[222:225], v[26:29]
	v_mfma_f32_16x16x32_bf16 v[10:13], v[170:173], v[230:233], v[10:13]
	v_mfma_f32_16x16x32_bf16 v[14:17], v[162:165], v[230:233], v[14:17]
	s_setprio 0
	s_setprio 1
	v_mfma_f32_16x16x32_bf16 v[54:57], v[174:177], v[202:205], v[54:57]
	v_mfma_f32_16x16x32_bf16 v[50:53], v[194:197], v[202:205], v[50:53]
	v_mfma_f32_16x16x32_bf16 v[34:37], v[194:197], v[210:213], v[34:37]
	v_mfma_f32_16x16x32_bf16 v[38:41], v[174:177], v[210:213], v[38:41]
	v_mfma_f32_16x16x32_bf16 v[22:25], v[174:177], v[218:221], v[22:25]
	v_mfma_f32_16x16x32_bf16 v[18:21], v[194:197], v[218:221], v[18:21]
	v_mfma_f32_16x16x32_bf16 v[2:5], v[194:197], v[226:229], v[2:5]
	v_mfma_f32_16x16x32_bf16 v[6:9], v[174:177], v[226:229], v[6:9]
	v_mfma_f32_16x16x32_bf16 v[54:57], v[190:193], v[206:209], v[54:57]
	v_mfma_f32_16x16x32_bf16 v[50:53], v[198:201], v[206:209], v[50:53]
	v_mfma_f32_16x16x32_bf16 v[34:37], v[198:201], v[214:217], v[34:37]
	v_mfma_f32_16x16x32_bf16 v[38:41], v[190:193], v[214:217], v[38:41]
	v_mfma_f32_16x16x32_bf16 v[22:25], v[190:193], v[222:225], v[22:25]
	v_mfma_f32_16x16x32_bf16 v[18:21], v[198:201], v[222:225], v[18:21]
	v_mfma_f32_16x16x32_bf16 v[2:5], v[198:201], v[230:233], v[2:5]
	v_mfma_f32_16x16x32_bf16 v[6:9], v[190:193], v[230:233], v[6:9]
	s_setprio 0
	s_barrier
	s_add_i32 s43, 0, 0x18000
	v_add_u32_e32 v138, s43, v181
	s_add_i32 s44, 0, 0x1c000
	ds_read_b128 v[158:161], v138
	ds_read_b128 v[162:165], v138 offset:1024
	ds_read_b128 v[166:169], v138 offset:2048
	ds_read_b128 v[170:173], v138 offset:3072
	v_add_u32_e32 v138, s44, v181
	ds_read_b128 v[174:177], v138
	ds_read_b128 v[190:193], v138 offset:1024
	ds_read_b128 v[194:197], v138 offset:2048
	ds_read_b128 v[198:201], v138 offset:3072
	s_add_u32 s40, s40, s8
	s_addc_u32 s41, s41, s9
	s_mov_b32 m0, s47
	v_lshl_add_u64 v[244:245], s[40:41], 0, v[136:137]
	ds_read_b128 v[202:205], v187 offset:32768
	ds_read_b128 v[206:209], v187 offset:33792
	ds_read_b128 v[210:213], v187 offset:34816
	ds_read_b128 v[214:217], v187 offset:35840
	ds_read_b128 v[218:221], v187 offset:36864
	ds_read_b128 v[222:225], v187 offset:37888
	ds_read_b128 v[226:229], v187 offset:38912
	ds_read_b128 v[230:233], v187 offset:39936
	global_load_lds_dwordx4 v[244:245], off
	v_lshl_add_u64 v[244:245], s[40:41], 0, v[132:133]
	s_mov_b32 m0, s48
	s_nop 0
	global_load_lds_dwordx4 v[244:245], off
	s_waitcnt vmcnt(8)
	s_waitcnt lgkmcnt(0)
	s_barrier
	s_setprio 1
	s_waitcnt lgkmcnt(0)
	v_mfma_f32_16x16x32_bf16 v[70:73], v[158:161], v[202:205], v[70:73]
	v_mfma_f32_16x16x32_bf16 v[66:69], v[166:169], v[202:205], v[66:69]
	v_mfma_f32_16x16x32_bf16 v[94:97], v[166:169], v[210:213], v[94:97]
	v_mfma_f32_16x16x32_bf16 v[86:89], v[158:161], v[210:213], v[86:89]
	v_mfma_f32_16x16x32_bf16 v[110:113], v[158:161], v[218:221], v[110:113]
	v_mfma_f32_16x16x32_bf16 v[114:117], v[166:169], v[218:221], v[114:117]
	v_mfma_f32_16x16x32_bf16 v[102:105], v[166:169], v[226:229], v[102:105]
	v_mfma_f32_16x16x32_bf16 v[126:129], v[158:161], v[226:229], v[126:129]
	v_mfma_f32_16x16x32_bf16 v[70:73], v[162:165], v[206:209], v[70:73]
	v_mfma_f32_16x16x32_bf16 v[66:69], v[170:173], v[206:209], v[66:69]
	v_mfma_f32_16x16x32_bf16 v[94:97], v[170:173], v[214:217], v[94:97]
	v_mfma_f32_16x16x32_bf16 v[86:89], v[162:165], v[214:217], v[86:89]
	v_mfma_f32_16x16x32_bf16 v[110:113], v[162:165], v[222:225], v[110:113]
	v_mfma_f32_16x16x32_bf16 v[114:117], v[170:173], v[222:225], v[114:117]
	v_mfma_f32_16x16x32_bf16 v[102:105], v[170:173], v[230:233], v[102:105]
	v_mfma_f32_16x16x32_bf16 v[126:129], v[162:165], v[230:233], v[126:129]
	s_setprio 0
	s_setprio 1
	v_mfma_f32_16x16x32_bf16 v[74:77], v[174:177], v[202:205], v[74:77]
	v_mfma_f32_16x16x32_bf16 v[82:85], v[194:197], v[202:205], v[82:85]
	v_mfma_f32_16x16x32_bf16 v[106:109], v[194:197], v[210:213], v[106:109]
	v_mfma_f32_16x16x32_bf16 v[98:101], v[174:177], v[210:213], v[98:101]
	v_mfma_f32_16x16x32_bf16 v[118:121], v[174:177], v[218:221], v[118:121]
	v_mfma_f32_16x16x32_bf16 v[122:125], v[194:197], v[218:221], v[122:125]
	v_mfma_f32_16x16x32_bf16 v[78:81], v[194:197], v[226:229], v[78:81]
	v_mfma_f32_16x16x32_bf16 v[90:93], v[174:177], v[226:229], v[90:93]
	v_mfma_f32_16x16x32_bf16 v[74:77], v[190:193], v[206:209], v[74:77]
	v_mfma_f32_16x16x32_bf16 v[82:85], v[198:201], v[206:209], v[82:85]
	v_mfma_f32_16x16x32_bf16 v[106:109], v[198:201], v[214:217], v[106:109]
	v_mfma_f32_16x16x32_bf16 v[98:101], v[190:193], v[214:217], v[98:101]
	v_mfma_f32_16x16x32_bf16 v[118:121], v[190:193], v[222:225], v[118:121]
	v_mfma_f32_16x16x32_bf16 v[122:125], v[198:201], v[222:225], v[122:125]
	v_mfma_f32_16x16x32_bf16 v[78:81], v[198:201], v[230:233], v[78:81]
	v_mfma_f32_16x16x32_bf16 v[90:93], v[190:193], v[230:233], v[90:93]
	s_setprio 0
	s_barrier
	s_add_i32 s40, s43, s4
	v_lshl_add_u64 v[182:183], v[182:183], 0, s[22:23]
	s_mov_b32 m0, s40
	ds_read_b128 v[202:205], v187 offset:49152
	ds_read_b128 v[206:209], v187 offset:50176
	ds_read_b128 v[210:213], v187 offset:51200
	ds_read_b128 v[214:217], v187 offset:52224
	ds_read_b128 v[218:221], v187 offset:53248
	ds_read_b128 v[222:225], v187 offset:54272
	ds_read_b128 v[226:229], v187 offset:55296
	ds_read_b128 v[230:233], v187 offset:56320
	global_load_lds_dwordx4 v[182:183], off
	v_lshl_add_u64 v[182:183], v[234:235], 0, s[22:23]
	s_add_i32 m0, s40, 0x2000
	s_add_i32 s40, s44, s4
	global_load_lds_dwordx4 v[182:183], off
	v_lshl_add_u64 v[182:183], v[236:237], 0, s[22:23]
	s_mov_b32 m0, s40
	s_nop 0
	global_load_lds_dwordx4 v[182:183], off
	v_lshl_add_u64 v[182:183], v[238:239], 0, s[22:23]
	s_add_i32 m0, s40, 0x2000
	s_nop 0
	global_load_lds_dwordx4 v[182:183], off
	v_lshl_add_u64 v[182:183], v[240:241], 0, s[22:23]
	s_mov_b32 m0, s49
	s_nop 0
	global_load_lds_dwordx4 v[182:183], off
	v_lshl_add_u64 v[182:183], v[242:243], 0, s[22:23]
	s_mov_b32 m0, s50
	s_nop 0
	global_load_lds_dwordx4 v[182:183], off
	s_waitcnt vmcnt(8)
	s_waitcnt lgkmcnt(0)
	s_barrier
	s_setprio 1
	s_waitcnt lgkmcnt(0)
	v_mfma_f32_16x16x32_bf16 v[62:65], v[158:161], v[202:205], v[62:65]
	v_mfma_f32_16x16x32_bf16 v[58:61], v[166:169], v[202:205], v[58:61]
	v_mfma_f32_16x16x32_bf16 v[42:45], v[166:169], v[210:213], v[42:45]
	v_mfma_f32_16x16x32_bf16 v[46:49], v[158:161], v[210:213], v[46:49]
	v_mfma_f32_16x16x32_bf16 v[30:33], v[158:161], v[218:221], v[30:33]
	v_mfma_f32_16x16x32_bf16 v[26:29], v[166:169], v[218:221], v[26:29]
	v_mfma_f32_16x16x32_bf16 v[10:13], v[166:169], v[226:229], v[10:13]
	v_mfma_f32_16x16x32_bf16 v[14:17], v[158:161], v[226:229], v[14:17]
	v_mfma_f32_16x16x32_bf16 v[62:65], v[162:165], v[206:209], v[62:65]
	v_mfma_f32_16x16x32_bf16 v[58:61], v[170:173], v[206:209], v[58:61]
	v_mfma_f32_16x16x32_bf16 v[42:45], v[170:173], v[214:217], v[42:45]
	v_mfma_f32_16x16x32_bf16 v[46:49], v[162:165], v[214:217], v[46:49]
	v_mfma_f32_16x16x32_bf16 v[30:33], v[162:165], v[222:225], v[30:33]
	v_mfma_f32_16x16x32_bf16 v[26:29], v[170:173], v[222:225], v[26:29]
	v_mfma_f32_16x16x32_bf16 v[10:13], v[170:173], v[230:233], v[10:13]
	v_mfma_f32_16x16x32_bf16 v[14:17], v[162:165], v[230:233], v[14:17]
	s_setprio 0
	s_setprio 1
	v_mfma_f32_16x16x32_bf16 v[54:57], v[174:177], v[202:205], v[54:57]
	v_mfma_f32_16x16x32_bf16 v[50:53], v[194:197], v[202:205], v[50:53]
	v_mfma_f32_16x16x32_bf16 v[34:37], v[194:197], v[210:213], v[34:37]
	v_mfma_f32_16x16x32_bf16 v[38:41], v[174:177], v[210:213], v[38:41]
	v_mfma_f32_16x16x32_bf16 v[22:25], v[174:177], v[218:221], v[22:25]
	v_mfma_f32_16x16x32_bf16 v[18:21], v[194:197], v[218:221], v[18:21]
	v_mfma_f32_16x16x32_bf16 v[2:5], v[194:197], v[226:229], v[2:5]
	v_mfma_f32_16x16x32_bf16 v[6:9], v[174:177], v[226:229], v[6:9]
	v_mfma_f32_16x16x32_bf16 v[54:57], v[190:193], v[206:209], v[54:57]
	v_mfma_f32_16x16x32_bf16 v[50:53], v[198:201], v[206:209], v[50:53]
	v_mfma_f32_16x16x32_bf16 v[34:37], v[198:201], v[214:217], v[34:37]
	v_mfma_f32_16x16x32_bf16 v[38:41], v[190:193], v[214:217], v[38:41]
	v_mfma_f32_16x16x32_bf16 v[22:25], v[190:193], v[222:225], v[22:25]
	v_mfma_f32_16x16x32_bf16 v[18:21], v[198:201], v[222:225], v[18:21]
	v_mfma_f32_16x16x32_bf16 v[2:5], v[198:201], v[230:233], v[2:5]
	v_mfma_f32_16x16x32_bf16 v[6:9], v[190:193], v[230:233], v[6:9]
	s_setprio 0
	s_barrier
	s_add_u32 s0, s0, 0x100
	s_addc_u32 s1, s1, 0
	s_cmp_ge_i32 s42, s51
	s_mov_b32 s40, s42
	s_cbranch_scc0 .LBB0_828

.LBB0_903:
	ds_read_b128 v[130:133], v209
	ds_read_b128 v[134:137], v209 offset:1024
	ds_read_b128 v[138:141], v209 offset:2048
	ds_read_b128 v[142:145], v209 offset:3072
	ds_read_b128 v[146:149], v210
	ds_read_b128 v[150:153], v210 offset:1024
	ds_read_b128 v[154:157], v210 offset:2048
	ds_read_b128 v[158:161], v210 offset:3072
	s_add_u32 s30, s28, 0xfffc0080
	s_addc_u32 s31, s29, -1
	s_cmp_eq_u32 s55, 12
	s_cselect_b32 s35, s1, s31
	s_cselect_b32 s34, s50, s30
	s_cselect_b32 s31, s51, s54
	s_cselect_b32 s30, s52, s53
	v_lshl_add_u64 v[216:217], s[28:29], 0, v[190:191]
	s_add_i32 m0, s39, 0xc000
	ds_read_b128 v[162:165], v211
	ds_read_b128 v[166:169], v211 offset:1024
	ds_read_b128 v[170:173], v211 offset:2048
	ds_read_b128 v[174:177], v211 offset:3072
	ds_read_b128 v[194:197], v211 offset:4096
	ds_read_b128 v[198:201], v211 offset:5120
	ds_read_b128 v[202:205], v211 offset:6144
	ds_read_b128 v[212:215], v211 offset:7168
	global_load_lds_dwordx4 v[216:217], off
	v_lshl_add_u64 v[216:217], s[28:29], 0, v[192:193]
	s_add_i32 m0, s39, 0xe000
	s_nop 0
	global_load_lds_dwordx4 v[216:217], off
	s_waitcnt vmcnt(8)
	s_waitcnt lgkmcnt(0)
	s_barrier
	s_setprio 1
	s_waitcnt lgkmcnt(0)
	v_mfma_f32_16x16x32_bf16 v[126:129], v[130:133], v[162:165], v[126:129]
	v_mfma_f32_16x16x32_bf16 v[122:125], v[138:141], v[162:165], v[122:125]
	v_mfma_f32_16x16x32_bf16 v[106:109], v[138:141], v[170:173], v[106:109]
	v_mfma_f32_16x16x32_bf16 v[110:113], v[130:133], v[170:173], v[110:113]
	v_mfma_f32_16x16x32_bf16 v[94:97], v[130:133], v[194:197], v[94:97]
	v_mfma_f32_16x16x32_bf16 v[90:93], v[138:141], v[194:197], v[90:93]
	v_mfma_f32_16x16x32_bf16 v[74:77], v[138:141], v[202:205], v[74:77]
	v_mfma_f32_16x16x32_bf16 v[78:81], v[130:133], v[202:205], v[78:81]
	v_mfma_f32_16x16x32_bf16 v[126:129], v[134:137], v[166:169], v[126:129]
	v_mfma_f32_16x16x32_bf16 v[122:125], v[142:145], v[166:169], v[122:125]
	v_mfma_f32_16x16x32_bf16 v[106:109], v[142:145], v[174:177], v[106:109]
	v_mfma_f32_16x16x32_bf16 v[110:113], v[134:137], v[174:177], v[110:113]
	v_mfma_f32_16x16x32_bf16 v[94:97], v[134:137], v[198:201], v[94:97]
	v_mfma_f32_16x16x32_bf16 v[90:93], v[142:145], v[198:201], v[90:93]
	v_mfma_f32_16x16x32_bf16 v[74:77], v[142:145], v[212:215], v[74:77]
	v_mfma_f32_16x16x32_bf16 v[78:81], v[134:137], v[212:215], v[78:81]
	s_setprio 0
	s_setprio 1
	v_mfma_f32_16x16x32_bf16 v[118:121], v[146:149], v[162:165], v[118:121]
	v_mfma_f32_16x16x32_bf16 v[114:117], v[154:157], v[162:165], v[114:117]
	v_mfma_f32_16x16x32_bf16 v[98:101], v[154:157], v[170:173], v[98:101]
	v_mfma_f32_16x16x32_bf16 v[102:105], v[146:149], v[170:173], v[102:105]
	v_mfma_f32_16x16x32_bf16 v[86:89], v[146:149], v[194:197], v[86:89]
	v_mfma_f32_16x16x32_bf16 v[82:85], v[154:157], v[194:197], v[82:85]
	v_mfma_f32_16x16x32_bf16 v[66:69], v[154:157], v[202:205], v[66:69]
	v_mfma_f32_16x16x32_bf16 v[70:73], v[146:149], v[202:205], v[70:73]
	v_mfma_f32_16x16x32_bf16 v[118:121], v[150:153], v[166:169], v[118:121]
	v_mfma_f32_16x16x32_bf16 v[114:117], v[158:161], v[166:169], v[114:117]
	v_mfma_f32_16x16x32_bf16 v[98:101], v[158:161], v[174:177], v[98:101]
	v_mfma_f32_16x16x32_bf16 v[102:105], v[150:153], v[174:177], v[102:105]
	v_mfma_f32_16x16x32_bf16 v[86:89], v[150:153], v[198:201], v[86:89]
	v_mfma_f32_16x16x32_bf16 v[82:85], v[158:161], v[198:201], v[82:85]
	v_mfma_f32_16x16x32_bf16 v[66:69], v[158:161], v[212:215], v[66:69]
	v_mfma_f32_16x16x32_bf16 v[70:73], v[150:153], v[212:215], v[70:73]
	s_setprio 0
	s_barrier
	s_add_i32 s56, s48, s38
	v_lshl_add_u64 v[216:217], s[30:31], 0, v[184:185]
	s_mov_b32 m0, s56
	ds_read_b128 v[162:165], v211 offset:16384
	ds_read_b128 v[166:169], v211 offset:17408
	ds_read_b128 v[170:173], v211 offset:18432
	ds_read_b128 v[174:177], v211 offset:19456
	ds_read_b128 v[194:197], v211 offset:20480
	ds_read_b128 v[198:201], v211 offset:21504
	ds_read_b128 v[202:205], v211 offset:22528
	ds_read_b128 v[212:215], v211 offset:23552
	global_load_lds_dwordx4 v[216:217], off
	s_add_i32 m0, s56, 0x2000
	s_add_u32 s56, s30, 0x40000
	v_lshl_add_u64 v[218:219], s[30:31], 0, v[188:189]
	s_addc_u32 s57, s31, 0
	s_add_i32 s58, s49, s38
	global_load_lds_dwordx4 v[218:219], off
	v_lshl_add_u64 v[220:221], s[56:57], 0, v[184:185]
	s_mov_b32 m0, s58
	v_lshl_add_u64 v[222:223], s[34:35], 0, v[186:187]
	global_load_lds_dwordx4 v[220:221], off
	v_lshl_add_u64 v[220:221], s[56:57], 0, v[188:189]
	s_add_i32 m0, s58, 0x2000
	s_nop 0
	global_load_lds_dwordx4 v[220:221], off
	v_lshl_add_u64 v[220:221], s[34:35], 0, v[182:183]
	s_mov_b32 m0, s39
	s_nop 0
	global_load_lds_dwordx4 v[220:221], off
	s_mov_b32 m0, s40
	s_nop 0
	global_load_lds_dwordx4 v[222:223], off
	s_waitcnt vmcnt(8)
	s_waitcnt lgkmcnt(0)
	s_barrier
	s_setprio 1
	s_waitcnt lgkmcnt(0)
	v_mfma_f32_16x16x32_bf16 v[62:65], v[130:133], v[162:165], v[62:65]
	v_mfma_f32_16x16x32_bf16 v[58:61], v[138:141], v[162:165], v[58:61]
	v_mfma_f32_16x16x32_bf16 v[42:45], v[138:141], v[170:173], v[42:45]
	v_mfma_f32_16x16x32_bf16 v[46:49], v[130:133], v[170:173], v[46:49]
	v_mfma_f32_16x16x32_bf16 v[30:33], v[130:133], v[194:197], v[30:33]
	v_mfma_f32_16x16x32_bf16 v[26:29], v[138:141], v[194:197], v[26:29]
	v_mfma_f32_16x16x32_bf16 v[10:13], v[138:141], v[202:205], v[10:13]
	v_mfma_f32_16x16x32_bf16 v[14:17], v[130:133], v[202:205], v[14:17]
	v_mfma_f32_16x16x32_bf16 v[62:65], v[134:137], v[166:169], v[62:65]
	v_mfma_f32_16x16x32_bf16 v[58:61], v[142:145], v[166:169], v[58:61]
	v_mfma_f32_16x16x32_bf16 v[42:45], v[142:145], v[174:177], v[42:45]
	v_mfma_f32_16x16x32_bf16 v[46:49], v[134:137], v[174:177], v[46:49]
	v_mfma_f32_16x16x32_bf16 v[30:33], v[134:137], v[198:201], v[30:33]
	v_mfma_f32_16x16x32_bf16 v[26:29], v[142:145], v[198:201], v[26:29]
	v_mfma_f32_16x16x32_bf16 v[10:13], v[142:145], v[212:215], v[10:13]
	v_mfma_f32_16x16x32_bf16 v[14:17], v[134:137], v[212:215], v[14:17]
	s_setprio 0
	s_setprio 1
	v_mfma_f32_16x16x32_bf16 v[54:57], v[146:149], v[162:165], v[54:57]
	v_mfma_f32_16x16x32_bf16 v[50:53], v[154:157], v[162:165], v[50:53]
	v_mfma_f32_16x16x32_bf16 v[34:37], v[154:157], v[170:173], v[34:37]
	v_mfma_f32_16x16x32_bf16 v[38:41], v[146:149], v[170:173], v[38:41]
	v_mfma_f32_16x16x32_bf16 v[22:25], v[146:149], v[194:197], v[22:25]
	v_mfma_f32_16x16x32_bf16 v[18:21], v[154:157], v[194:197], v[18:21]
	v_mfma_f32_16x16x32_bf16 v[2:5], v[154:157], v[202:205], v[2:5]
	v_mfma_f32_16x16x32_bf16 v[6:9], v[146:149], v[202:205], v[6:9]
	v_mfma_f32_16x16x32_bf16 v[54:57], v[150:153], v[166:169], v[54:57]
	v_mfma_f32_16x16x32_bf16 v[50:53], v[158:161], v[166:169], v[50:53]
	v_mfma_f32_16x16x32_bf16 v[34:37], v[158:161], v[174:177], v[34:37]
	v_mfma_f32_16x16x32_bf16 v[38:41], v[150:153], v[174:177], v[38:41]
	v_mfma_f32_16x16x32_bf16 v[22:25], v[150:153], v[198:201], v[22:25]
	v_mfma_f32_16x16x32_bf16 v[18:21], v[158:161], v[198:201], v[18:21]
	v_mfma_f32_16x16x32_bf16 v[2:5], v[158:161], v[212:215], v[2:5]
	v_mfma_f32_16x16x32_bf16 v[6:9], v[150:153], v[212:215], v[6:9]
	s_setprio 0
	s_barrier
	s_add_i32 s56, 0, 0x18000
	s_add_i32 s57, 0, 0x1c000
	v_add_u32_e32 v142, s56, v207
	v_add_u32_e32 v158, s57, v207
	ds_read_b128 v[130:133], v142
	ds_read_b128 v[134:137], v142 offset:1024
	ds_read_b128 v[138:141], v142 offset:2048
	ds_read_b128 v[142:145], v142 offset:3072
	ds_read_b128 v[146:149], v158
	ds_read_b128 v[150:153], v158 offset:1024
	ds_read_b128 v[154:157], v158 offset:2048
	ds_read_b128 v[158:161], v158 offset:3072
	s_add_u32 s34, s34, 0x40000
	s_addc_u32 s35, s35, 0
	s_mov_b32 m0, s41
	v_lshl_add_u64 v[224:225], s[34:35], 0, v[182:183]
	ds_read_b128 v[162:165], v211 offset:32768
	ds_read_b128 v[166:169], v211 offset:33792
	ds_read_b128 v[170:173], v211 offset:34816
	ds_read_b128 v[174:177], v211 offset:35840
	ds_read_b128 v[194:197], v211 offset:36864
	ds_read_b128 v[198:201], v211 offset:37888
	ds_read_b128 v[202:205], v211 offset:38912
	ds_read_b128 v[212:215], v211 offset:39936
	global_load_lds_dwordx4 v[224:225], off
	v_lshl_add_u64 v[224:225], s[34:35], 0, v[186:187]
	s_mov_b32 m0, s42
	s_nop 0
	global_load_lds_dwordx4 v[224:225], off
	s_waitcnt vmcnt(8)
	s_waitcnt lgkmcnt(0)
	s_barrier
	s_setprio 1
	s_waitcnt lgkmcnt(0)
	v_mfma_f32_16x16x32_bf16 v[126:129], v[130:133], v[162:165], v[126:129]
	v_mfma_f32_16x16x32_bf16 v[122:125], v[138:141], v[162:165], v[122:125]
	v_mfma_f32_16x16x32_bf16 v[106:109], v[138:141], v[170:173], v[106:109]
	v_mfma_f32_16x16x32_bf16 v[110:113], v[130:133], v[170:173], v[110:113]
	v_mfma_f32_16x16x32_bf16 v[94:97], v[130:133], v[194:197], v[94:97]
	v_mfma_f32_16x16x32_bf16 v[90:93], v[138:141], v[194:197], v[90:93]
	v_mfma_f32_16x16x32_bf16 v[74:77], v[138:141], v[202:205], v[74:77]
	v_mfma_f32_16x16x32_bf16 v[78:81], v[130:133], v[202:205], v[78:81]
	v_mfma_f32_16x16x32_bf16 v[126:129], v[134:137], v[166:169], v[126:129]
	v_mfma_f32_16x16x32_bf16 v[122:125], v[142:145], v[166:169], v[122:125]
	v_mfma_f32_16x16x32_bf16 v[106:109], v[142:145], v[174:177], v[106:109]
	v_mfma_f32_16x16x32_bf16 v[110:113], v[134:137], v[174:177], v[110:113]
	v_mfma_f32_16x16x32_bf16 v[94:97], v[134:137], v[198:201], v[94:97]
	v_mfma_f32_16x16x32_bf16 v[90:93], v[142:145], v[198:201], v[90:93]
	v_mfma_f32_16x16x32_bf16 v[74:77], v[142:145], v[212:215], v[74:77]
	v_mfma_f32_16x16x32_bf16 v[78:81], v[134:137], v[212:215], v[78:81]
	s_setprio 0
	s_setprio 1
	v_mfma_f32_16x16x32_bf16 v[118:121], v[146:149], v[162:165], v[118:121]
	v_mfma_f32_16x16x32_bf16 v[114:117], v[154:157], v[162:165], v[114:117]
	v_mfma_f32_16x16x32_bf16 v[98:101], v[154:157], v[170:173], v[98:101]
	v_mfma_f32_16x16x32_bf16 v[102:105], v[146:149], v[170:173], v[102:105]
	v_mfma_f32_16x16x32_bf16 v[86:89], v[146:149], v[194:197], v[86:89]
	v_mfma_f32_16x16x32_bf16 v[82:85], v[154:157], v[194:197], v[82:85]
	v_mfma_f32_16x16x32_bf16 v[66:69], v[154:157], v[202:205], v[66:69]
	v_mfma_f32_16x16x32_bf16 v[70:73], v[146:149], v[202:205], v[70:73]
	v_mfma_f32_16x16x32_bf16 v[118:121], v[150:153], v[166:169], v[118:121]
	v_mfma_f32_16x16x32_bf16 v[114:117], v[158:161], v[166:169], v[114:117]
	v_mfma_f32_16x16x32_bf16 v[98:101], v[158:161], v[174:177], v[98:101]
	v_mfma_f32_16x16x32_bf16 v[102:105], v[150:153], v[174:177], v[102:105]
	v_mfma_f32_16x16x32_bf16 v[86:89], v[150:153], v[198:201], v[86:89]
	v_mfma_f32_16x16x32_bf16 v[82:85], v[158:161], v[198:201], v[82:85]
	v_mfma_f32_16x16x32_bf16 v[66:69], v[158:161], v[212:215], v[66:69]
	v_mfma_f32_16x16x32_bf16 v[70:73], v[150:153], v[212:215], v[70:73]
	s_setprio 0
	s_barrier
	s_add_i32 s34, s56, s38
	v_lshl_add_u64 v[216:217], v[216:217], 0, s[22:23]
	s_mov_b32 m0, s34
	ds_read_b128 v[162:165], v211 offset:49152
	ds_read_b128 v[166:169], v211 offset:50176
	ds_read_b128 v[170:173], v211 offset:51200
	ds_read_b128 v[174:177], v211 offset:52224
	ds_read_b128 v[194:197], v211 offset:53248
	ds_read_b128 v[198:201], v211 offset:54272
	ds_read_b128 v[202:205], v211 offset:55296
	ds_read_b128 v[212:215], v211 offset:56320
	global_load_lds_dwordx4 v[216:217], off
	s_add_i32 m0, s34, 0x2000
	s_add_u32 s30, s30, 0x40080
	v_lshl_add_u64 v[216:217], v[218:219], 0, s[22:23]
	s_addc_u32 s31, s31, 0
	s_add_i32 s34, s57, s38
	global_load_lds_dwordx4 v[216:217], off
	v_lshl_add_u64 v[216:217], s[30:31], 0, v[184:185]
	s_mov_b32 m0, s34
	s_nop 0
	global_load_lds_dwordx4 v[216:217], off
	v_lshl_add_u64 v[216:217], s[30:31], 0, v[188:189]
	s_add_i32 m0, s34, 0x2000
	s_nop 0
	global_load_lds_dwordx4 v[216:217], off
	v_lshl_add_u64 v[216:217], v[220:221], 0, s[22:23]
	s_mov_b32 m0, s44
	s_nop 0
	global_load_lds_dwordx4 v[216:217], off
	v_lshl_add_u64 v[216:217], v[222:223], 0, s[22:23]
	s_mov_b32 m0, s45
	s_nop 0
	global_load_lds_dwordx4 v[216:217], off
	s_waitcnt vmcnt(8)
	s_waitcnt lgkmcnt(0)
	s_barrier
	s_setprio 1
	s_waitcnt lgkmcnt(0)
	v_mfma_f32_16x16x32_bf16 v[62:65], v[130:133], v[162:165], v[62:65]
	v_mfma_f32_16x16x32_bf16 v[58:61], v[138:141], v[162:165], v[58:61]
	v_mfma_f32_16x16x32_bf16 v[42:45], v[138:141], v[170:173], v[42:45]
	v_mfma_f32_16x16x32_bf16 v[46:49], v[130:133], v[170:173], v[46:49]
	v_mfma_f32_16x16x32_bf16 v[30:33], v[130:133], v[194:197], v[30:33]
	v_mfma_f32_16x16x32_bf16 v[26:29], v[138:141], v[194:197], v[26:29]
	v_mfma_f32_16x16x32_bf16 v[10:13], v[138:141], v[202:205], v[10:13]
	v_mfma_f32_16x16x32_bf16 v[14:17], v[130:133], v[202:205], v[14:17]
	v_mfma_f32_16x16x32_bf16 v[62:65], v[134:137], v[166:169], v[62:65]
	v_mfma_f32_16x16x32_bf16 v[58:61], v[142:145], v[166:169], v[58:61]
	v_mfma_f32_16x16x32_bf16 v[42:45], v[142:145], v[174:177], v[42:45]
	v_mfma_f32_16x16x32_bf16 v[46:49], v[134:137], v[174:177], v[46:49]
	v_mfma_f32_16x16x32_bf16 v[30:33], v[134:137], v[198:201], v[30:33]
	v_mfma_f32_16x16x32_bf16 v[26:29], v[142:145], v[198:201], v[26:29]
	v_mfma_f32_16x16x32_bf16 v[10:13], v[142:145], v[212:215], v[10:13]
	v_mfma_f32_16x16x32_bf16 v[14:17], v[134:137], v[212:215], v[14:17]
	s_setprio 0
	s_setprio 1
	v_mfma_f32_16x16x32_bf16 v[54:57], v[146:149], v[162:165], v[54:57]
	v_mfma_f32_16x16x32_bf16 v[50:53], v[154:157], v[162:165], v[50:53]
	v_mfma_f32_16x16x32_bf16 v[34:37], v[154:157], v[170:173], v[34:37]
	v_mfma_f32_16x16x32_bf16 v[38:41], v[146:149], v[170:173], v[38:41]
	v_mfma_f32_16x16x32_bf16 v[22:25], v[146:149], v[194:197], v[22:25]
	v_mfma_f32_16x16x32_bf16 v[18:21], v[154:157], v[194:197], v[18:21]
	v_mfma_f32_16x16x32_bf16 v[2:5], v[154:157], v[202:205], v[2:5]
	v_mfma_f32_16x16x32_bf16 v[6:9], v[146:149], v[202:205], v[6:9]
	v_mfma_f32_16x16x32_bf16 v[54:57], v[150:153], v[166:169], v[54:57]
	v_mfma_f32_16x16x32_bf16 v[50:53], v[158:161], v[166:169], v[50:53]
	v_mfma_f32_16x16x32_bf16 v[34:37], v[158:161], v[174:177], v[34:37]
	v_mfma_f32_16x16x32_bf16 v[38:41], v[150:153], v[174:177], v[38:41]
	v_mfma_f32_16x16x32_bf16 v[22:25], v[150:153], v[198:201], v[22:25]
	v_mfma_f32_16x16x32_bf16 v[18:21], v[158:161], v[198:201], v[18:21]
	v_mfma_f32_16x16x32_bf16 v[2:5], v[158:161], v[212:215], v[2:5]
	v_mfma_f32_16x16x32_bf16 v[6:9], v[150:153], v[212:215], v[6:9]
	s_setprio 0
	s_barrier
	s_add_i32 s55, s55, 2
	s_add_u32 s28, s28, 0x100
	s_addc_u32 s29, s29, 0
	s_add_u32 s53, s53, 0x100
	s_addc_u32 s54, s54, 0
	s_cmp_gt_u32 s55, 13
	s_cbranch_scc0 .LBB0_903
	s_and_b64 vcc, exec, s[24:25]
	s_cbranch_vccz .LBB0_906
	s_barrier

.LBB0_991:
	ds_read_b128 v[66:69], v219
	ds_read_b128 v[70:73], v219 offset:1024
	ds_read_b128 v[86:89], v219 offset:2048
	ds_read_b128 v[106:109], v219 offset:3072
	ds_read_b128 v[146:149], v220
	ds_read_b128 v[150:153], v220 offset:1024
	ds_read_b128 v[154:157], v220 offset:2048
	ds_read_b128 v[158:161], v220 offset:3072
	s_add_u32 s10, s8, 0xfffc0080
	s_addc_u32 s11, s9, -1
	s_cmp_eq_u32 s22, 12
	s_cselect_b32 s45, s1, s11
	s_cselect_b32 s44, s2, s10
	s_cselect_b32 s11, s3, s7
	s_cselect_b32 s10, s4, s5
	v_lshl_add_u64 v[224:225], s[8:9], 0, v[192:193]
	s_add_i32 m0, s54, 0xc000
	ds_read_b128 v[162:165], v221
	ds_read_b128 v[166:169], v221 offset:1024
	ds_read_b128 v[170:173], v221 offset:2048
	ds_read_b128 v[174:177], v221 offset:3072
	ds_read_b128 v[196:199], v221 offset:4096
	ds_read_b128 v[200:203], v221 offset:5120
	ds_read_b128 v[204:207], v221 offset:6144
	ds_read_b128 v[208:211], v221 offset:7168
	global_load_lds_dwordx4 v[224:225], off
	v_lshl_add_u64 v[224:225], s[8:9], 0, v[194:195]
	s_add_i32 m0, s54, 0xe000
	s_nop 0
	global_load_lds_dwordx4 v[224:225], off
	s_waitcnt vmcnt(8)
	s_waitcnt lgkmcnt(0)
	s_barrier
	s_setprio 1
	s_waitcnt lgkmcnt(0)
	v_mfma_f32_16x16x32_bf16 v[142:145], v[66:69], v[162:165], v[142:145]
	v_mfma_f32_16x16x32_bf16 v[134:137], v[86:89], v[162:165], v[134:137]
	v_mfma_f32_16x16x32_bf16 v[122:125], v[86:89], v[170:173], v[122:125]
	v_mfma_f32_16x16x32_bf16 v[126:129], v[66:69], v[170:173], v[126:129]
	v_mfma_f32_16x16x32_bf16 v[110:113], v[66:69], v[196:199], v[110:113]
	v_mfma_f32_16x16x32_bf16 v[102:105], v[86:89], v[196:199], v[102:105]
	v_mfma_f32_16x16x32_bf16 v[82:85], v[86:89], v[204:207], v[82:85]
	v_mfma_f32_16x16x32_bf16 v[90:93], v[66:69], v[204:207], v[90:93]
	v_mfma_f32_16x16x32_bf16 v[142:145], v[70:73], v[166:169], v[142:145]
	v_mfma_f32_16x16x32_bf16 v[134:137], v[106:109], v[166:169], v[134:137]
	v_mfma_f32_16x16x32_bf16 v[122:125], v[106:109], v[174:177], v[122:125]
	v_mfma_f32_16x16x32_bf16 v[126:129], v[70:73], v[174:177], v[126:129]
	v_mfma_f32_16x16x32_bf16 v[110:113], v[70:73], v[200:203], v[110:113]
	v_mfma_f32_16x16x32_bf16 v[102:105], v[106:109], v[200:203], v[102:105]
	v_mfma_f32_16x16x32_bf16 v[82:85], v[106:109], v[208:211], v[82:85]
	v_mfma_f32_16x16x32_bf16 v[90:93], v[70:73], v[208:211], v[90:93]
	s_setprio 0
	s_setprio 1
	v_mfma_f32_16x16x32_bf16 v[138:141], v[146:149], v[162:165], v[138:141]
	v_mfma_f32_16x16x32_bf16 v[130:133], v[154:157], v[162:165], v[130:133]
	v_mfma_f32_16x16x32_bf16 v[114:117], v[154:157], v[170:173], v[114:117]
	v_mfma_f32_16x16x32_bf16 v[118:121], v[146:149], v[170:173], v[118:121]
	v_mfma_f32_16x16x32_bf16 v[98:101], v[146:149], v[196:199], v[98:101]
	v_mfma_f32_16x16x32_bf16 v[94:97], v[154:157], v[196:199], v[94:97]
	v_mfma_f32_16x16x32_bf16 v[74:77], v[154:157], v[204:207], v[74:77]
	v_mfma_f32_16x16x32_bf16 v[78:81], v[146:149], v[204:207], v[78:81]
	v_mfma_f32_16x16x32_bf16 v[138:141], v[150:153], v[166:169], v[138:141]
	v_mfma_f32_16x16x32_bf16 v[130:133], v[158:161], v[166:169], v[130:133]
	v_mfma_f32_16x16x32_bf16 v[114:117], v[158:161], v[174:177], v[114:117]
	v_mfma_f32_16x16x32_bf16 v[118:121], v[150:153], v[174:177], v[118:121]
	v_mfma_f32_16x16x32_bf16 v[98:101], v[150:153], v[200:203], v[98:101]
	v_mfma_f32_16x16x32_bf16 v[94:97], v[158:161], v[200:203], v[94:97]
	v_mfma_f32_16x16x32_bf16 v[74:77], v[158:161], v[208:211], v[74:77]
	v_mfma_f32_16x16x32_bf16 v[78:81], v[150:153], v[208:211], v[78:81]
	s_setprio 0
	s_barrier
	s_add_i32 s37, s62, s53
	v_lshl_add_u64 v[224:225], s[10:11], 0, v[184:185]
	s_mov_b32 m0, s37
	ds_read_b128 v[162:165], v221 offset:16384
	ds_read_b128 v[166:169], v221 offset:17408
	ds_read_b128 v[170:173], v221 offset:18432
	ds_read_b128 v[174:177], v221 offset:19456
	ds_read_b128 v[196:199], v221 offset:20480
	ds_read_b128 v[200:203], v221 offset:21504
	ds_read_b128 v[204:207], v221 offset:22528
	ds_read_b128 v[208:211], v221 offset:23552
	global_load_lds_dwordx4 v[224:225], off
	s_add_i32 m0, s37, 0x2000
	s_add_u32 s46, s10, 0x40000
	v_lshl_add_u64 v[226:227], s[10:11], 0, v[188:189]
	s_addc_u32 s47, s11, 0
	s_add_i32 s37, s63, s53
	global_load_lds_dwordx4 v[226:227], off
	v_lshl_add_u64 v[228:229], s[46:47], 0, v[184:185]
	s_mov_b32 m0, s37
	v_lshl_add_u64 v[230:231], s[44:45], 0, v[186:187]
	global_load_lds_dwordx4 v[228:229], off
	v_lshl_add_u64 v[228:229], s[46:47], 0, v[188:189]
	s_add_i32 m0, s37, 0x2000
	s_nop 0
	global_load_lds_dwordx4 v[228:229], off
	v_lshl_add_u64 v[228:229], s[44:45], 0, v[182:183]
	s_mov_b32 m0, s54
	s_nop 0
	global_load_lds_dwordx4 v[228:229], off
	s_mov_b32 m0, s55
	s_nop 0
	global_load_lds_dwordx4 v[230:231], off
	s_waitcnt vmcnt(8)
	s_waitcnt lgkmcnt(0)
	s_barrier
	s_setprio 1
	s_waitcnt lgkmcnt(0)
	v_mfma_f32_16x16x32_bf16 v[62:65], v[66:69], v[162:165], v[62:65]
	v_mfma_f32_16x16x32_bf16 v[54:57], v[86:89], v[162:165], v[54:57]
	v_mfma_f32_16x16x32_bf16 v[42:45], v[86:89], v[170:173], v[42:45]
	v_mfma_f32_16x16x32_bf16 v[46:49], v[66:69], v[170:173], v[46:49]
	v_mfma_f32_16x16x32_bf16 v[30:33], v[66:69], v[196:199], v[30:33]
	v_mfma_f32_16x16x32_bf16 v[26:29], v[86:89], v[196:199], v[26:29]
	v_mfma_f32_16x16x32_bf16 v[10:13], v[86:89], v[204:207], v[10:13]
	v_mfma_f32_16x16x32_bf16 v[14:17], v[66:69], v[204:207], v[14:17]
	v_mfma_f32_16x16x32_bf16 v[62:65], v[70:73], v[166:169], v[62:65]
	v_mfma_f32_16x16x32_bf16 v[54:57], v[106:109], v[166:169], v[54:57]
	v_mfma_f32_16x16x32_bf16 v[42:45], v[106:109], v[174:177], v[42:45]
	v_mfma_f32_16x16x32_bf16 v[46:49], v[70:73], v[174:177], v[46:49]
	v_mfma_f32_16x16x32_bf16 v[30:33], v[70:73], v[200:203], v[30:33]
	v_mfma_f32_16x16x32_bf16 v[26:29], v[106:109], v[200:203], v[26:29]
	v_mfma_f32_16x16x32_bf16 v[10:13], v[106:109], v[208:211], v[10:13]
	v_mfma_f32_16x16x32_bf16 v[14:17], v[70:73], v[208:211], v[14:17]
	s_setprio 0
	s_setprio 1
	v_mfma_f32_16x16x32_bf16 v[58:61], v[146:149], v[162:165], v[58:61]
	v_mfma_f32_16x16x32_bf16 v[50:53], v[154:157], v[162:165], v[50:53]
	v_mfma_f32_16x16x32_bf16 v[34:37], v[154:157], v[170:173], v[34:37]
	v_mfma_f32_16x16x32_bf16 v[38:41], v[146:149], v[170:173], v[38:41]
	v_mfma_f32_16x16x32_bf16 v[22:25], v[146:149], v[196:199], v[22:25]
	v_mfma_f32_16x16x32_bf16 v[18:21], v[154:157], v[196:199], v[18:21]
	v_mfma_f32_16x16x32_bf16 v[2:5], v[154:157], v[204:207], v[2:5]
	v_mfma_f32_16x16x32_bf16 v[6:9], v[146:149], v[204:207], v[6:9]
	v_mfma_f32_16x16x32_bf16 v[58:61], v[150:153], v[166:169], v[58:61]
	v_mfma_f32_16x16x32_bf16 v[50:53], v[158:161], v[166:169], v[50:53]
	v_mfma_f32_16x16x32_bf16 v[34:37], v[158:161], v[174:177], v[34:37]
	v_mfma_f32_16x16x32_bf16 v[38:41], v[150:153], v[174:177], v[38:41]
	v_mfma_f32_16x16x32_bf16 v[22:25], v[150:153], v[200:203], v[22:25]
	v_mfma_f32_16x16x32_bf16 v[18:21], v[158:161], v[200:203], v[18:21]
	v_mfma_f32_16x16x32_bf16 v[2:5], v[158:161], v[208:211], v[2:5]
	v_mfma_f32_16x16x32_bf16 v[6:9], v[150:153], v[208:211], v[6:9]
	s_setprio 0
	s_barrier
	s_add_i32 s37, 0, 0x18000
	s_add_i32 s39, 0, 0x1c000
	v_add_u32_e32 v106, s37, v213
	v_add_u32_e32 v158, s39, v213
	ds_read_b128 v[66:69], v106
	ds_read_b128 v[70:73], v106 offset:1024
	ds_read_b128 v[86:89], v106 offset:2048
	ds_read_b128 v[106:109], v106 offset:3072
	ds_read_b128 v[146:149], v158
	ds_read_b128 v[150:153], v158 offset:1024
	ds_read_b128 v[154:157], v158 offset:2048
	ds_read_b128 v[158:161], v158 offset:3072
	s_add_u32 s44, s44, 0x40000
	s_addc_u32 s45, s45, 0
	s_mov_b32 m0, s56
	v_lshl_add_u64 v[232:233], s[44:45], 0, v[182:183]
	ds_read_b128 v[162:165], v221 offset:32768
	ds_read_b128 v[166:169], v221 offset:33792
	ds_read_b128 v[170:173], v221 offset:34816
	ds_read_b128 v[174:177], v221 offset:35840
	ds_read_b128 v[196:199], v221 offset:36864
	ds_read_b128 v[200:203], v221 offset:37888
	ds_read_b128 v[204:207], v221 offset:38912
	ds_read_b128 v[208:211], v221 offset:39936
	global_load_lds_dwordx4 v[232:233], off
	v_lshl_add_u64 v[232:233], s[44:45], 0, v[186:187]
	s_mov_b32 m0, s57
	s_nop 0
	global_load_lds_dwordx4 v[232:233], off
	s_waitcnt vmcnt(8)
	s_waitcnt lgkmcnt(0)
	s_barrier
	s_setprio 1
	s_waitcnt lgkmcnt(0)
	v_mfma_f32_16x16x32_bf16 v[142:145], v[66:69], v[162:165], v[142:145]
	v_mfma_f32_16x16x32_bf16 v[134:137], v[86:89], v[162:165], v[134:137]
	v_mfma_f32_16x16x32_bf16 v[122:125], v[86:89], v[170:173], v[122:125]
	v_mfma_f32_16x16x32_bf16 v[126:129], v[66:69], v[170:173], v[126:129]
	v_mfma_f32_16x16x32_bf16 v[110:113], v[66:69], v[196:199], v[110:113]
	v_mfma_f32_16x16x32_bf16 v[102:105], v[86:89], v[196:199], v[102:105]
	v_mfma_f32_16x16x32_bf16 v[82:85], v[86:89], v[204:207], v[82:85]
	v_mfma_f32_16x16x32_bf16 v[90:93], v[66:69], v[204:207], v[90:93]
	v_mfma_f32_16x16x32_bf16 v[142:145], v[70:73], v[166:169], v[142:145]
	v_mfma_f32_16x16x32_bf16 v[134:137], v[106:109], v[166:169], v[134:137]
	v_mfma_f32_16x16x32_bf16 v[122:125], v[106:109], v[174:177], v[122:125]
	v_mfma_f32_16x16x32_bf16 v[126:129], v[70:73], v[174:177], v[126:129]
	v_mfma_f32_16x16x32_bf16 v[110:113], v[70:73], v[200:203], v[110:113]
	v_mfma_f32_16x16x32_bf16 v[102:105], v[106:109], v[200:203], v[102:105]
	v_mfma_f32_16x16x32_bf16 v[82:85], v[106:109], v[208:211], v[82:85]
	v_mfma_f32_16x16x32_bf16 v[90:93], v[70:73], v[208:211], v[90:93]
	s_setprio 0
	s_setprio 1
	v_mfma_f32_16x16x32_bf16 v[138:141], v[146:149], v[162:165], v[138:141]
	v_mfma_f32_16x16x32_bf16 v[130:133], v[154:157], v[162:165], v[130:133]
	v_mfma_f32_16x16x32_bf16 v[114:117], v[154:157], v[170:173], v[114:117]
	v_mfma_f32_16x16x32_bf16 v[118:121], v[146:149], v[170:173], v[118:121]
	v_mfma_f32_16x16x32_bf16 v[98:101], v[146:149], v[196:199], v[98:101]
	v_mfma_f32_16x16x32_bf16 v[94:97], v[154:157], v[196:199], v[94:97]
	v_mfma_f32_16x16x32_bf16 v[74:77], v[154:157], v[204:207], v[74:77]
	v_mfma_f32_16x16x32_bf16 v[78:81], v[146:149], v[204:207], v[78:81]
	v_mfma_f32_16x16x32_bf16 v[138:141], v[150:153], v[166:169], v[138:141]
	v_mfma_f32_16x16x32_bf16 v[130:133], v[158:161], v[166:169], v[130:133]
	v_mfma_f32_16x16x32_bf16 v[114:117], v[158:161], v[174:177], v[114:117]
	v_mfma_f32_16x16x32_bf16 v[118:121], v[150:153], v[174:177], v[118:121]
	v_mfma_f32_16x16x32_bf16 v[98:101], v[150:153], v[200:203], v[98:101]
	v_mfma_f32_16x16x32_bf16 v[94:97], v[158:161], v[200:203], v[94:97]
	v_mfma_f32_16x16x32_bf16 v[74:77], v[158:161], v[208:211], v[74:77]
	v_mfma_f32_16x16x32_bf16 v[78:81], v[150:153], v[208:211], v[78:81]
	s_setprio 0
	s_barrier
	s_add_i32 s37, s37, s53
	v_lshl_add_u64 v[224:225], v[224:225], 0, s[28:29]
	s_mov_b32 m0, s37
	ds_read_b128 v[162:165], v221 offset:49152
	ds_read_b128 v[166:169], v221 offset:50176
	ds_read_b128 v[170:173], v221 offset:51200
	ds_read_b128 v[174:177], v221 offset:52224
	ds_read_b128 v[196:199], v221 offset:53248
	ds_read_b128 v[200:203], v221 offset:54272
	ds_read_b128 v[204:207], v221 offset:55296
	ds_read_b128 v[208:211], v221 offset:56320
	global_load_lds_dwordx4 v[224:225], off
	s_add_i32 m0, s37, 0x2000
	s_add_u32 s10, s10, 0x40080
	v_lshl_add_u64 v[224:225], v[226:227], 0, s[28:29]
	s_addc_u32 s11, s11, 0
	s_add_i32 s37, s39, s53
	global_load_lds_dwordx4 v[224:225], off
	v_lshl_add_u64 v[224:225], s[10:11], 0, v[184:185]
	s_mov_b32 m0, s37
	s_nop 0
	global_load_lds_dwordx4 v[224:225], off
	v_lshl_add_u64 v[224:225], s[10:11], 0, v[188:189]
	s_add_i32 m0, s37, 0x2000
	s_nop 0
	global_load_lds_dwordx4 v[224:225], off
	v_lshl_add_u64 v[224:225], v[228:229], 0, s[28:29]
	s_mov_b32 m0, s60
	s_nop 0
	global_load_lds_dwordx4 v[224:225], off
	v_lshl_add_u64 v[224:225], v[230:231], 0, s[28:29]
	s_mov_b32 m0, s61
	s_nop 0
	global_load_lds_dwordx4 v[224:225], off
	s_waitcnt vmcnt(8)
	s_waitcnt lgkmcnt(0)
	s_barrier
	s_setprio 1
	s_waitcnt lgkmcnt(0)
	v_mfma_f32_16x16x32_bf16 v[62:65], v[66:69], v[162:165], v[62:65]
	v_mfma_f32_16x16x32_bf16 v[54:57], v[86:89], v[162:165], v[54:57]
	v_mfma_f32_16x16x32_bf16 v[42:45], v[86:89], v[170:173], v[42:45]
	v_mfma_f32_16x16x32_bf16 v[46:49], v[66:69], v[170:173], v[46:49]
	v_mfma_f32_16x16x32_bf16 v[30:33], v[66:69], v[196:199], v[30:33]
	v_mfma_f32_16x16x32_bf16 v[26:29], v[86:89], v[196:199], v[26:29]
	v_mfma_f32_16x16x32_bf16 v[10:13], v[86:89], v[204:207], v[10:13]
	v_mfma_f32_16x16x32_bf16 v[14:17], v[66:69], v[204:207], v[14:17]
	v_mfma_f32_16x16x32_bf16 v[62:65], v[70:73], v[166:169], v[62:65]
	v_mfma_f32_16x16x32_bf16 v[54:57], v[106:109], v[166:169], v[54:57]
	v_mfma_f32_16x16x32_bf16 v[42:45], v[106:109], v[174:177], v[42:45]
	v_mfma_f32_16x16x32_bf16 v[46:49], v[70:73], v[174:177], v[46:49]
	v_mfma_f32_16x16x32_bf16 v[30:33], v[70:73], v[200:203], v[30:33]
	v_mfma_f32_16x16x32_bf16 v[26:29], v[106:109], v[200:203], v[26:29]
	v_mfma_f32_16x16x32_bf16 v[10:13], v[106:109], v[208:211], v[10:13]
	v_mfma_f32_16x16x32_bf16 v[14:17], v[70:73], v[208:211], v[14:17]
	s_setprio 0
	s_setprio 1
	v_mfma_f32_16x16x32_bf16 v[58:61], v[146:149], v[162:165], v[58:61]
	v_mfma_f32_16x16x32_bf16 v[50:53], v[154:157], v[162:165], v[50:53]
	v_mfma_f32_16x16x32_bf16 v[34:37], v[154:157], v[170:173], v[34:37]
	v_mfma_f32_16x16x32_bf16 v[38:41], v[146:149], v[170:173], v[38:41]
	v_mfma_f32_16x16x32_bf16 v[22:25], v[146:149], v[196:199], v[22:25]
	v_mfma_f32_16x16x32_bf16 v[18:21], v[154:157], v[196:199], v[18:21]
	v_mfma_f32_16x16x32_bf16 v[2:5], v[154:157], v[204:207], v[2:5]
	v_mfma_f32_16x16x32_bf16 v[6:9], v[146:149], v[204:207], v[6:9]
	v_mfma_f32_16x16x32_bf16 v[58:61], v[150:153], v[166:169], v[58:61]
	v_mfma_f32_16x16x32_bf16 v[50:53], v[158:161], v[166:169], v[50:53]
	v_mfma_f32_16x16x32_bf16 v[34:37], v[158:161], v[174:177], v[34:37]
	v_mfma_f32_16x16x32_bf16 v[38:41], v[150:153], v[174:177], v[38:41]
	v_mfma_f32_16x16x32_bf16 v[22:25], v[150:153], v[200:203], v[22:25]
	v_mfma_f32_16x16x32_bf16 v[18:21], v[158:161], v[200:203], v[18:21]
	v_mfma_f32_16x16x32_bf16 v[2:5], v[158:161], v[208:211], v[2:5]
	v_mfma_f32_16x16x32_bf16 v[6:9], v[150:153], v[208:211], v[6:9]
	s_setprio 0
	s_barrier
	s_add_i32 s22, s22, 2
	s_add_u32 s8, s8, 0x100
	s_addc_u32 s9, s9, 0
	s_add_u32 s5, s5, 0x100
	s_addc_u32 s7, s7, 0
	s_cmp_gt_u32 s22, 13
	s_cbranch_scc0 .LBB0_991
	s_and_b64 vcc, exec, s[30:31]
	s_cbranch_vccz .LBB0_994
.LBB0_994:
	s_sub_i32 s1, s58, s6
	s_mul_i32 s1, s1, 22
	s_add_i32 s1, s0, s1
	s_add_i32 s1, s1, 22
	s_ashr_i32 s1, s1, 2
	s_and_b32 s37, s1, 1
	s_lshl_b32 s2, s37, 2
	v_lshl_add_u32 v210, s6, 8, v212
	s_add_i32 s2, s2, 0
	s_add_i32 s2, s2, 0x201a0
	v_or_b32_e32 v208, 16, v210
	v_mov_b32_e32 v66, s2
	v_ashrrev_i32_e32 v211, 31, v210
	v_ashrrev_i32_e32 v209, 31, v208
	ds_read_b32 v146, v66
	v_lshlrev_b64 v[66:67], 6, v[210:211]
	v_lshlrev_b64 v[68:69], 6, v[208:209]
	v_or_b32_e32 v206, 32, v210
	v_or_b32_e32 v204, 48, v210
	v_lshl_add_u64 v[66:67], v[190:191], 0, v[66:67]
	v_lshl_add_u64 v[68:69], v[190:191], 0, v[68:69]
	v_ashrrev_i32_e32 v207, 31, v206
	v_ashrrev_i32_e32 v205, 31, v204
	global_load_dwordx4 v[174:177], v[66:67], off
	global_load_dwordx4 v[170:173], v[68:69], off
	v_lshlrev_b64 v[66:67], 6, v[206:207]
	v_lshlrev_b64 v[68:69], 6, v[204:205]
	v_add_u32_e32 v202, 0x80, v210
	v_add_u32_e32 v200, 0x90, v210
	v_lshl_add_u64 v[66:67], v[190:191], 0, v[66:67]
	v_lshl_add_u64 v[68:69], v[190:191], 0, v[68:69]
	v_ashrrev_i32_e32 v203, 31, v202
	v_ashrrev_i32_e32 v201, 31, v200
	global_load_dwordx4 v[166:169], v[66:67], off
	global_load_dwordx4 v[162:165], v[68:69], off
	v_lshlrev_b64 v[66:67], 6, v[202:203]
	v_lshlrev_b64 v[68:69], 6, v[200:201]
	v_add_u32_e32 v198, 0xa0, v210
	v_add_u32_e32 v196, 0xb0, v210
	v_lshl_add_u64 v[66:67], v[190:191], 0, v[66:67]
	v_lshl_add_u64 v[68:69], v[190:191], 0, v[68:69]
	v_ashrrev_i32_e32 v199, 31, v198
	v_ashrrev_i32_e32 v197, 31, v196
	global_load_dwordx4 v[106:109], v[66:67], off
	global_load_dwordx4 v[86:89], v[68:69], off
	v_lshlrev_b64 v[66:67], 6, v[198:199]
	v_lshlrev_b64 v[68:69], 6, v[196:197]
	v_lshl_add_u64 v[66:67], v[190:191], 0, v[66:67]
	v_lshl_add_u64 v[68:69], v[190:191], 0, v[68:69]
	global_load_dwordx4 v[70:73], v[66:67], off
	s_nop 0
	global_load_dwordx4 v[66:69], v[68:69], off
	s_waitcnt lgkmcnt(0)
	v_readfirstlane_b32 s2, v146
	v_cmp_lt_i32_e32 vcc, s66, v146
	v_mov_b32_e32 v153, 0
	v_cmp_gt_i32_e64 s[6:7], s65, v146
	s_and_b64 vcc, exec, vcc
	v_mov_b32_e32 v152, 0
	v_mov_b32_e32 v151, 0
	v_mov_b32_e32 v150, 0
	v_mov_b32_e32 v157, 0
	v_mov_b32_e32 v156, 0
	v_mov_b32_e32 v155, 0
	v_mov_b32_e32 v154, 0
	v_mov_b32_e32 v149, 0
	v_mov_b32_e32 v148, 0
	v_mov_b32_e32 v147, 0
	v_mov_b32_e32 v146, 0
	v_mov_b32_e32 v161, 0
	v_mov_b32_e32 v160, 0
	v_mov_b32_e32 v159, 0
	v_mov_b32_e32 v158, 0
	s_bitcmp1_b32 s30, 0
	s_cbranch_scc0 .Lae4_skip
	s_barrier
.Lae4_skip:
	s_cbranch_vccnz .Ls4_nocp
	s_cmpk_lt_u32 s2, 0xf8
	s_cbranch_scc0 .Lcpl4_a
	s_mov_b32 s4, s2
	s_mov_b32 s5, 0x8421085
	s_movk_i32 s22, 0x3e00
	s_movk_i32 s39, 0x200
	s_mov_b64 s[8:9], s[12:13]
	s_add_u32 s100, s20, 0x8280000
	s_addc_u32 s101, s21, 0
	s_branch .Lcpl4_go

.LBB0_1108:
	ds_read_b128 v[142:145], v150
	ds_read_b128 v[156:159], v150 offset:1024
	ds_read_b128 v[160:163], v150 offset:2048
	ds_read_b128 v[164:167], v150 offset:3072
	ds_read_b128 v[168:171], v151
	ds_read_b128 v[172:175], v151 offset:1024
	ds_read_b128 v[180:183], v151 offset:2048
	ds_read_b128 v[184:187], v151 offset:3072
	s_add_u32 s24, s22, 0xfff50080
	s_addc_u32 s25, s23, -1
	s_cmp_eq_u32 s51, 40
	s_cselect_b32 s27, s21, s25
	s_cselect_b32 s26, s20, s24
	s_cselect_b32 s25, s19, s50
	s_cselect_b32 s24, s18, s49
	s_mov_b32 m0, s36
	v_lshl_add_u64 v[146:147], s[22:23], 0, v[138:139]
	ds_read_b128 v[188:191], v152
	ds_read_b128 v[192:195], v152 offset:1024
	ds_read_b128 v[196:199], v152 offset:2048
	ds_read_b128 v[200:203], v152 offset:3072
	ds_read_b128 v[204:207], v152 offset:4096
	ds_read_b128 v[208:211], v152 offset:5120
	ds_read_b128 v[212:215], v152 offset:6144
	ds_read_b128 v[216:219], v152 offset:7168
	global_load_lds_dwordx4 v[146:147], off
	v_lshl_add_u64 v[146:147], s[22:23], 0, v[140:141]
	s_mov_b32 m0, s37
	s_nop 0
	global_load_lds_dwordx4 v[146:147], off
	s_waitcnt vmcnt(8)
	s_waitcnt lgkmcnt(0)
	s_barrier
	s_setprio 1
	s_waitcnt lgkmcnt(0)
	v_mfma_f32_16x16x32_bf16 v[126:129], v[142:145], v[188:191], v[126:129]
	v_mfma_f32_16x16x32_bf16 v[122:125], v[160:163], v[188:191], v[122:125]
	v_mfma_f32_16x16x32_bf16 v[106:109], v[160:163], v[196:199], v[106:109]
	v_mfma_f32_16x16x32_bf16 v[110:113], v[142:145], v[196:199], v[110:113]
	v_mfma_f32_16x16x32_bf16 v[94:97], v[142:145], v[204:207], v[94:97]
	v_mfma_f32_16x16x32_bf16 v[90:93], v[160:163], v[204:207], v[90:93]
	v_mfma_f32_16x16x32_bf16 v[74:77], v[160:163], v[212:215], v[74:77]
	v_mfma_f32_16x16x32_bf16 v[78:81], v[142:145], v[212:215], v[78:81]
	v_mfma_f32_16x16x32_bf16 v[126:129], v[156:159], v[192:195], v[126:129]
	v_mfma_f32_16x16x32_bf16 v[122:125], v[164:167], v[192:195], v[122:125]
	v_mfma_f32_16x16x32_bf16 v[106:109], v[164:167], v[200:203], v[106:109]
	v_mfma_f32_16x16x32_bf16 v[110:113], v[156:159], v[200:203], v[110:113]
	v_mfma_f32_16x16x32_bf16 v[94:97], v[156:159], v[208:211], v[94:97]
	v_mfma_f32_16x16x32_bf16 v[90:93], v[164:167], v[208:211], v[90:93]
	v_mfma_f32_16x16x32_bf16 v[74:77], v[164:167], v[216:219], v[74:77]
	v_mfma_f32_16x16x32_bf16 v[78:81], v[156:159], v[216:219], v[78:81]
	s_setprio 0
	s_setprio 1
	v_mfma_f32_16x16x32_bf16 v[118:121], v[168:171], v[188:191], v[118:121]
	v_mfma_f32_16x16x32_bf16 v[114:117], v[180:183], v[188:191], v[114:117]
	v_mfma_f32_16x16x32_bf16 v[98:101], v[180:183], v[196:199], v[98:101]
	v_mfma_f32_16x16x32_bf16 v[102:105], v[168:171], v[196:199], v[102:105]
	v_mfma_f32_16x16x32_bf16 v[86:89], v[168:171], v[204:207], v[86:89]
	v_mfma_f32_16x16x32_bf16 v[82:85], v[180:183], v[204:207], v[82:85]
	v_mfma_f32_16x16x32_bf16 v[66:69], v[180:183], v[212:215], v[66:69]
	v_mfma_f32_16x16x32_bf16 v[70:73], v[168:171], v[212:215], v[70:73]
	v_mfma_f32_16x16x32_bf16 v[118:121], v[172:175], v[192:195], v[118:121]
	v_mfma_f32_16x16x32_bf16 v[114:117], v[184:187], v[192:195], v[114:117]
	v_mfma_f32_16x16x32_bf16 v[98:101], v[184:187], v[200:203], v[98:101]
	v_mfma_f32_16x16x32_bf16 v[102:105], v[172:175], v[200:203], v[102:105]
	v_mfma_f32_16x16x32_bf16 v[86:89], v[172:175], v[208:211], v[86:89]
	v_mfma_f32_16x16x32_bf16 v[82:85], v[184:187], v[208:211], v[82:85]
	v_mfma_f32_16x16x32_bf16 v[66:69], v[184:187], v[216:219], v[66:69]
	v_mfma_f32_16x16x32_bf16 v[70:73], v[172:175], v[216:219], v[70:73]
	s_setprio 0
	s_barrier
	s_mov_b32 m0, s38
	v_lshl_add_u64 v[146:147], s[24:25], 0, v[134:135]
	s_add_u32 s52, s24, 0xb0000
	ds_read_b128 v[188:191], v152 offset:16384
	ds_read_b128 v[192:195], v152 offset:17408
	ds_read_b128 v[196:199], v152 offset:18432
	ds_read_b128 v[200:203], v152 offset:19456
	ds_read_b128 v[204:207], v152 offset:20480
	ds_read_b128 v[208:211], v152 offset:21504
	ds_read_b128 v[212:215], v152 offset:22528
	ds_read_b128 v[216:219], v152 offset:23552
	global_load_lds_dwordx4 v[146:147], off
	v_lshl_add_u64 v[176:177], s[24:25], 0, v[130:131]
	s_mov_b32 m0, s39
	s_addc_u32 s53, s25, 0
	global_load_lds_dwordx4 v[176:177], off
	v_lshl_add_u64 v[220:221], s[52:53], 0, v[134:135]
	s_mov_b32 m0, s40
	v_lshl_add_u64 v[222:223], s[26:27], 0, v[132:133]
	global_load_lds_dwordx4 v[220:221], off
	v_lshl_add_u64 v[220:221], s[52:53], 0, v[130:131]
	s_mov_b32 m0, s41
	s_nop 0
	global_load_lds_dwordx4 v[220:221], off
	v_lshl_add_u64 v[220:221], s[26:27], 0, v[136:137]
	s_mov_b32 m0, s4
	s_nop 0
	global_load_lds_dwordx4 v[220:221], off
	s_mov_b32 m0, s5
	s_nop 0
	global_load_lds_dwordx4 v[222:223], off
	s_waitcnt vmcnt(8)
	s_waitcnt lgkmcnt(0)
	s_barrier
	s_setprio 1
	s_waitcnt lgkmcnt(0)
	v_mfma_f32_16x16x32_bf16 v[62:65], v[142:145], v[188:191], v[62:65]
	v_mfma_f32_16x16x32_bf16 v[58:61], v[160:163], v[188:191], v[58:61]
	v_mfma_f32_16x16x32_bf16 v[42:45], v[160:163], v[196:199], v[42:45]
	v_mfma_f32_16x16x32_bf16 v[46:49], v[142:145], v[196:199], v[46:49]
	v_mfma_f32_16x16x32_bf16 v[34:37], v[142:145], v[204:207], v[34:37]
	v_mfma_f32_16x16x32_bf16 v[26:29], v[160:163], v[204:207], v[26:29]
	v_mfma_f32_16x16x32_bf16 v[10:13], v[160:163], v[212:215], v[10:13]
	v_mfma_f32_16x16x32_bf16 v[18:21], v[142:145], v[212:215], v[18:21]
	v_mfma_f32_16x16x32_bf16 v[62:65], v[156:159], v[192:195], v[62:65]
	v_mfma_f32_16x16x32_bf16 v[58:61], v[164:167], v[192:195], v[58:61]
	v_mfma_f32_16x16x32_bf16 v[42:45], v[164:167], v[200:203], v[42:45]
	v_mfma_f32_16x16x32_bf16 v[46:49], v[156:159], v[200:203], v[46:49]
	v_mfma_f32_16x16x32_bf16 v[34:37], v[156:159], v[208:211], v[34:37]
	v_mfma_f32_16x16x32_bf16 v[26:29], v[164:167], v[208:211], v[26:29]
	v_mfma_f32_16x16x32_bf16 v[10:13], v[164:167], v[216:219], v[10:13]
	v_mfma_f32_16x16x32_bf16 v[18:21], v[156:159], v[216:219], v[18:21]
	s_setprio 0
	s_setprio 1
	v_mfma_f32_16x16x32_bf16 v[54:57], v[168:171], v[188:191], v[54:57]
	v_mfma_f32_16x16x32_bf16 v[50:53], v[180:183], v[188:191], v[50:53]
	v_mfma_f32_16x16x32_bf16 v[30:33], v[180:183], v[196:199], v[30:33]
	v_mfma_f32_16x16x32_bf16 v[38:41], v[168:171], v[196:199], v[38:41]
	v_mfma_f32_16x16x32_bf16 v[22:25], v[168:171], v[204:207], v[22:25]
	v_mfma_f32_16x16x32_bf16 v[14:17], v[180:183], v[204:207], v[14:17]
	v_mfma_f32_16x16x32_bf16 v[2:5], v[180:183], v[212:215], v[2:5]
	v_mfma_f32_16x16x32_bf16 v[6:9], v[168:171], v[212:215], v[6:9]
	v_mfma_f32_16x16x32_bf16 v[54:57], v[172:175], v[192:195], v[54:57]
	v_mfma_f32_16x16x32_bf16 v[50:53], v[184:187], v[192:195], v[50:53]
	v_mfma_f32_16x16x32_bf16 v[30:33], v[184:187], v[200:203], v[30:33]
	v_mfma_f32_16x16x32_bf16 v[38:41], v[172:175], v[200:203], v[38:41]
	v_mfma_f32_16x16x32_bf16 v[22:25], v[172:175], v[208:211], v[22:25]
	v_mfma_f32_16x16x32_bf16 v[14:17], v[184:187], v[208:211], v[14:17]
	v_mfma_f32_16x16x32_bf16 v[2:5], v[184:187], v[216:219], v[2:5]
	v_mfma_f32_16x16x32_bf16 v[6:9], v[172:175], v[216:219], v[6:9]
	s_setprio 0
	s_barrier
	ds_read_b128 v[142:145], v153
	ds_read_b128 v[156:159], v153 offset:1024
	ds_read_b128 v[160:163], v153 offset:2048
	ds_read_b128 v[164:167], v153 offset:3072
	ds_read_b128 v[168:171], v154
	ds_read_b128 v[172:175], v154 offset:1024
	ds_read_b128 v[180:183], v154 offset:2048
	ds_read_b128 v[184:187], v154 offset:3072
	s_add_u32 s26, s26, 0xb0000
	s_addc_u32 s27, s27, 0
	s_mov_b32 m0, s29
	v_lshl_add_u64 v[224:225], s[26:27], 0, v[136:137]
	ds_read_b128 v[188:191], v152 offset:32768
	ds_read_b128 v[192:195], v152 offset:33792
	ds_read_b128 v[196:199], v152 offset:34816
	ds_read_b128 v[200:203], v152 offset:35840
	ds_read_b128 v[204:207], v152 offset:36864
	ds_read_b128 v[208:211], v152 offset:37888
	ds_read_b128 v[212:215], v152 offset:38912
	ds_read_b128 v[216:219], v152 offset:39936
	global_load_lds_dwordx4 v[224:225], off
	v_lshl_add_u64 v[224:225], s[26:27], 0, v[132:133]
	s_mov_b32 m0, s30
	s_nop 0
	global_load_lds_dwordx4 v[224:225], off
	s_waitcnt vmcnt(8)
	s_waitcnt lgkmcnt(0)
	s_barrier
	s_setprio 1
	s_waitcnt lgkmcnt(0)
	v_mfma_f32_16x16x32_bf16 v[126:129], v[142:145], v[188:191], v[126:129]
	v_mfma_f32_16x16x32_bf16 v[122:125], v[160:163], v[188:191], v[122:125]
	v_mfma_f32_16x16x32_bf16 v[106:109], v[160:163], v[196:199], v[106:109]
	v_mfma_f32_16x16x32_bf16 v[110:113], v[142:145], v[196:199], v[110:113]
	v_mfma_f32_16x16x32_bf16 v[94:97], v[142:145], v[204:207], v[94:97]
	v_mfma_f32_16x16x32_bf16 v[90:93], v[160:163], v[204:207], v[90:93]
	v_mfma_f32_16x16x32_bf16 v[74:77], v[160:163], v[212:215], v[74:77]
	v_mfma_f32_16x16x32_bf16 v[78:81], v[142:145], v[212:215], v[78:81]
	v_mfma_f32_16x16x32_bf16 v[126:129], v[156:159], v[192:195], v[126:129]
	v_mfma_f32_16x16x32_bf16 v[122:125], v[164:167], v[192:195], v[122:125]
	v_mfma_f32_16x16x32_bf16 v[106:109], v[164:167], v[200:203], v[106:109]
	v_mfma_f32_16x16x32_bf16 v[110:113], v[156:159], v[200:203], v[110:113]
	v_mfma_f32_16x16x32_bf16 v[94:97], v[156:159], v[208:211], v[94:97]
	v_mfma_f32_16x16x32_bf16 v[90:93], v[164:167], v[208:211], v[90:93]
	v_mfma_f32_16x16x32_bf16 v[74:77], v[164:167], v[216:219], v[74:77]
	v_mfma_f32_16x16x32_bf16 v[78:81], v[156:159], v[216:219], v[78:81]
	s_setprio 0
	s_setprio 1
	v_mfma_f32_16x16x32_bf16 v[118:121], v[168:171], v[188:191], v[118:121]
	v_mfma_f32_16x16x32_bf16 v[114:117], v[180:183], v[188:191], v[114:117]
	v_mfma_f32_16x16x32_bf16 v[98:101], v[180:183], v[196:199], v[98:101]
	v_mfma_f32_16x16x32_bf16 v[102:105], v[168:171], v[196:199], v[102:105]
	v_mfma_f32_16x16x32_bf16 v[86:89], v[168:171], v[204:207], v[86:89]
	v_mfma_f32_16x16x32_bf16 v[82:85], v[180:183], v[204:207], v[82:85]
	v_mfma_f32_16x16x32_bf16 v[66:69], v[180:183], v[212:215], v[66:69]
	v_mfma_f32_16x16x32_bf16 v[70:73], v[168:171], v[212:215], v[70:73]
	v_mfma_f32_16x16x32_bf16 v[118:121], v[172:175], v[192:195], v[118:121]
	v_mfma_f32_16x16x32_bf16 v[114:117], v[184:187], v[192:195], v[114:117]
	v_mfma_f32_16x16x32_bf16 v[98:101], v[184:187], v[200:203], v[98:101]
	v_mfma_f32_16x16x32_bf16 v[102:105], v[172:175], v[200:203], v[102:105]
	v_mfma_f32_16x16x32_bf16 v[86:89], v[172:175], v[208:211], v[86:89]
	v_mfma_f32_16x16x32_bf16 v[82:85], v[184:187], v[208:211], v[82:85]
	v_mfma_f32_16x16x32_bf16 v[66:69], v[184:187], v[216:219], v[66:69]
	v_mfma_f32_16x16x32_bf16 v[70:73], v[172:175], v[216:219], v[70:73]
	s_setprio 0
	s_barrier
	s_mov_b32 m0, s42
	v_lshl_add_u64 v[146:147], v[146:147], 0, s[14:15]
	s_add_u32 s24, s24, 0xb0080
	ds_read_b128 v[188:191], v152 offset:49152
	ds_read_b128 v[192:195], v152 offset:50176
	ds_read_b128 v[196:199], v152 offset:51200
	ds_read_b128 v[200:203], v152 offset:52224
	ds_read_b128 v[204:207], v152 offset:53248
	ds_read_b128 v[208:211], v152 offset:54272
	ds_read_b128 v[212:215], v152 offset:55296
	ds_read_b128 v[216:219], v152 offset:56320
	global_load_lds_dwordx4 v[146:147], off
	v_lshl_add_u64 v[146:147], v[176:177], 0, s[14:15]
	s_mov_b32 m0, s43
	s_addc_u32 s25, s25, 0
	global_load_lds_dwordx4 v[146:147], off
	v_lshl_add_u64 v[146:147], s[24:25], 0, v[134:135]
	s_mov_b32 m0, s44
	s_nop 0
	global_load_lds_dwordx4 v[146:147], off
	v_lshl_add_u64 v[146:147], s[24:25], 0, v[130:131]
	s_mov_b32 m0, s45
	s_nop 0
	global_load_lds_dwordx4 v[146:147], off
	v_lshl_add_u64 v[146:147], v[220:221], 0, s[14:15]
	s_mov_b32 m0, s0
	s_nop 0
	global_load_lds_dwordx4 v[146:147], off
	v_lshl_add_u64 v[146:147], v[222:223], 0, s[14:15]
	s_mov_b32 m0, s1
	s_nop 0
	global_load_lds_dwordx4 v[146:147], off
	s_waitcnt vmcnt(8)
	s_waitcnt lgkmcnt(0)
	s_barrier
	s_setprio 1
	s_waitcnt lgkmcnt(0)
	v_mfma_f32_16x16x32_bf16 v[62:65], v[142:145], v[188:191], v[62:65]
	v_mfma_f32_16x16x32_bf16 v[58:61], v[160:163], v[188:191], v[58:61]
	v_mfma_f32_16x16x32_bf16 v[42:45], v[160:163], v[196:199], v[42:45]
	v_mfma_f32_16x16x32_bf16 v[46:49], v[142:145], v[196:199], v[46:49]
	v_mfma_f32_16x16x32_bf16 v[34:37], v[142:145], v[204:207], v[34:37]
	v_mfma_f32_16x16x32_bf16 v[26:29], v[160:163], v[204:207], v[26:29]
	v_mfma_f32_16x16x32_bf16 v[10:13], v[160:163], v[212:215], v[10:13]
	v_mfma_f32_16x16x32_bf16 v[18:21], v[142:145], v[212:215], v[18:21]
	v_mfma_f32_16x16x32_bf16 v[62:65], v[156:159], v[192:195], v[62:65]
	v_mfma_f32_16x16x32_bf16 v[58:61], v[164:167], v[192:195], v[58:61]
	v_mfma_f32_16x16x32_bf16 v[42:45], v[164:167], v[200:203], v[42:45]
	v_mfma_f32_16x16x32_bf16 v[46:49], v[156:159], v[200:203], v[46:49]
	v_mfma_f32_16x16x32_bf16 v[34:37], v[156:159], v[208:211], v[34:37]
	v_mfma_f32_16x16x32_bf16 v[26:29], v[164:167], v[208:211], v[26:29]
	v_mfma_f32_16x16x32_bf16 v[10:13], v[164:167], v[216:219], v[10:13]
	v_mfma_f32_16x16x32_bf16 v[18:21], v[156:159], v[216:219], v[18:21]
	s_setprio 0
	s_setprio 1
	v_mfma_f32_16x16x32_bf16 v[54:57], v[168:171], v[188:191], v[54:57]
	v_mfma_f32_16x16x32_bf16 v[50:53], v[180:183], v[188:191], v[50:53]
	v_mfma_f32_16x16x32_bf16 v[30:33], v[180:183], v[196:199], v[30:33]
	v_mfma_f32_16x16x32_bf16 v[38:41], v[168:171], v[196:199], v[38:41]
	v_mfma_f32_16x16x32_bf16 v[22:25], v[168:171], v[204:207], v[22:25]
	v_mfma_f32_16x16x32_bf16 v[14:17], v[180:183], v[204:207], v[14:17]
	v_mfma_f32_16x16x32_bf16 v[2:5], v[180:183], v[212:215], v[2:5]
	v_mfma_f32_16x16x32_bf16 v[6:9], v[168:171], v[212:215], v[6:9]
	v_mfma_f32_16x16x32_bf16 v[54:57], v[172:175], v[192:195], v[54:57]
	v_mfma_f32_16x16x32_bf16 v[50:53], v[184:187], v[192:195], v[50:53]
	v_mfma_f32_16x16x32_bf16 v[30:33], v[184:187], v[200:203], v[30:33]
	v_mfma_f32_16x16x32_bf16 v[38:41], v[172:175], v[200:203], v[38:41]
	v_mfma_f32_16x16x32_bf16 v[22:25], v[172:175], v[208:211], v[22:25]
	v_mfma_f32_16x16x32_bf16 v[14:17], v[184:187], v[208:211], v[14:17]
	v_mfma_f32_16x16x32_bf16 v[2:5], v[184:187], v[216:219], v[2:5]
	v_mfma_f32_16x16x32_bf16 v[6:9], v[172:175], v[216:219], v[6:9]
	s_setprio 0
	s_barrier
	s_add_i32 s51, s51, 2
	s_add_u32 s22, s22, 0x100
	s_addc_u32 s23, s23, 0
	s_add_u32 s49, s49, 0x100
	s_addc_u32 s50, s50, 0
	s_cmp_gt_u32 s51, 41
	s_cbranch_scc0 .LBB0_1108
	s_and_b64 vcc, exec, s[16:17]
	s_cbranch_vccz .LBB0_1111
	s_barrier
